# v024 + gelu polynomial constant moved to a VGPR once per tile epilogue instead of once per block
# speedup vs baseline: 1.0032x; 1.0032x over previous
; __device__ __forceinline__ unsigned pk_bf16(float lo, float hi) { f32x2 v = {lo, hi}; bf16x2_t b = __builtin_convertvector(v, bf16x2_t); return __builtin_bit_cast(unsigned, b); }
; __device__ __forceinline__ f32x4 gelu4(f32x4 v) { f32x2 a = gelu_pk((f32x2){v[0], v[1]}), b = gelu_pk((f32x2){v[2], v[3]}); return (f32x4){a.x, a.y, b.x, b.y}; }
; __device__ __forceinline__ f32x2 gelu_pk(f32x2 v) {
;     const f32x2 av = __builtin_elementwise_abs(v), d = av * 0.2316418882f + 1.0f;
;     f32x2 t; t.x = __builtin_amdgcn_rcpf(d.x); t.y = __builtin_amdgcn_rcpf(d.y);
;     f32x2 q = t * 0.5307027145f + (-0.7265760135f); q = q * t + 0.7107068705f; q = q * t + (-0.142248368f); q = q * t + 0.127414796f; q = q * t;
;     const f32x2 s = (v * v) * (-0.72134752044f);
;     f32x2 e; e.x = __builtin_amdgcn_exp2f(s.x); e.y = __builtin_amdgcn_exp2f(s.y);
;     const f32x2 m = v * (q * e), r = v - m;
;     f32x2 o; o.x = v.x < 0.f ? m.x : r.x; o.y = v.y < 0.f ? m.y : r.y; return o;
; }
;     __device__ __forceinline__ void operator()(const f32x4 (&acc)[2][2][4][2], const Unit& u, int wr, int wc, int fr, int fq, float rp0, float rp1, const f32x4& raw0, const f32x4& raw1, float& rn0, float& rn1) const {
;     ...
;                 for (int m = 0; m < 4; ++m) {
;                     const int roff = ai * HALF + m * 16; const float r = rs[m];
; #pragma unroll
;                     for (int bj = 0; bj < 2; ++bj) {
;                         f32x4 v0 = acc[ai][bj][m][0] * r, v1 = acc[ai][bj][m][1] * r;
;                         if (gel) { v0 = gelu4(v0); v1 = gelu4(v1); }
;                         u32x4 w; w.x = pk_bf16(v0[0], v0[1]); w.y = pk_bf16(v0[2], v0[3]); w.z = pk_bf16(v1[0], v1[1]); w.w = pk_bf16(v1[2], v1[3]);
;                         *(u32x4*)(base + (size_t)roff * ld + bj * 32) = w;
;                     }
.LBB0_134:
	v_mov_b32_e32 v161, v160
	v_cvt_pk_bf16_f32 v177, v166, v167
	v_mov_b32_e32 v166, v160
	v_mov_b32_e32 v167, v160
	v_cndmask_b32_e64 v139, 0, 1, s[40:41]
	v_cvt_pk_bf16_f32 v174, v164, v165
	v_cvt_pk_bf16_f32 v175, v162, v163
	v_cvt_pk_bf16_f32 v176, v168, v169
	v_pk_mul_f32 v[162:163], v[124:125], v[166:167]
	v_pk_mul_f32 v[164:165], v[122:123], v[160:161]
	v_pk_mul_f32 v[166:167], v[128:129], v[166:167]
	v_cmp_ne_u32_e64 s[6:7], 1, v139
	s_andn2_b64 vcc, exec, s[40:41]
	v_pk_mul_f32 v[160:161], v[126:127], v[160:161]
	global_store_dwordx4 v[156:157], v[174:177], off
	s_cbranch_vccnz .LBB0_136
	v_fma_f32 v220, |v164|, s88, 1.0
	v_fma_f32 v221, |v165|, s88, 1.0
	v_fma_f32 v226, |v162|, s88, 1.0
	v_fma_f32 v227, |v163|, s88, 1.0
	v_pk_mul_f32 v[224:225], v[164:165], v[164:165]
	v_pk_mul_f32 v[230:231], v[162:163], v[162:163]
	v_rcp_f32_e32 v220, v220
	v_rcp_f32_e32 v221, v221
	v_rcp_f32_e32 v226, v226
	v_rcp_f32_e32 v227, v227
	v_pk_mul_f32 v[224:225], v[224:225], s[72:73] op_sel_hi:[1,0]
	v_pk_mul_f32 v[230:231], v[230:231], s[72:73] op_sel_hi:[1,0]
	v_pk_fma_f32 v[222:223], v[220:221], s[90:91], v[232:233] op_sel_hi:[1,0,0]
	v_pk_fma_f32 v[228:229], v[226:227], s[90:91], v[232:233] op_sel_hi:[1,0,0]
	v_exp_f32_e32 v224, v224
	v_exp_f32_e32 v225, v225
	v_exp_f32_e32 v230, v230
	v_exp_f32_e32 v231, v231
	v_pk_fma_f32 v[222:223], v[220:221], v[222:223], s[94:95] op_sel_hi:[1,1,0]
	v_pk_fma_f32 v[228:229], v[226:227], v[228:229], s[94:95] op_sel_hi:[1,1,0]
	v_pk_fma_f32 v[222:223], v[220:221], v[222:223], s[96:97] op_sel_hi:[1,1,0]
	v_pk_fma_f32 v[228:229], v[226:227], v[228:229], s[96:97] op_sel_hi:[1,1,0]
	v_pk_fma_f32 v[222:223], v[220:221], v[222:223], s[98:99] op_sel_hi:[1,1,0]
	v_pk_fma_f32 v[228:229], v[226:227], v[228:229], s[98:99] op_sel_hi:[1,1,0]
	v_pk_mul_f32 v[222:223], v[220:221], v[222:223]
	v_pk_mul_f32 v[228:229], v[226:227], v[228:229]
	v_pk_mul_f32 v[222:223], v[224:225], v[222:223]
	v_pk_mul_f32 v[228:229], v[230:231], v[228:229]
	v_max_f32_e32 v220, 0, v164
	v_max_f32_e32 v221, 0, v165
	v_max_f32_e32 v226, 0, v162
	v_max_f32_e32 v227, 0, v163
	v_fma_f32 v164, -|v164|, v222, v220
	v_fma_f32 v165, -|v165|, v223, v221
	v_fma_f32 v162, -|v162|, v228, v226
	v_fma_f32 v163, -|v163|, v229, v227
	v_fma_f32 v220, |v160|, s88, 1.0
	v_fma_f32 v221, |v161|, s88, 1.0
	v_fma_f32 v226, |v166|, s88, 1.0
	v_fma_f32 v227, |v167|, s88, 1.0
	v_pk_mul_f32 v[224:225], v[160:161], v[160:161]
	v_pk_mul_f32 v[230:231], v[166:167], v[166:167]
	v_rcp_f32_e32 v220, v220
	v_rcp_f32_e32 v221, v221
	v_rcp_f32_e32 v226, v226
	v_rcp_f32_e32 v227, v227
	v_pk_mul_f32 v[224:225], v[224:225], s[72:73] op_sel_hi:[1,0]
	v_pk_mul_f32 v[230:231], v[230:231], s[72:73] op_sel_hi:[1,0]
	v_pk_fma_f32 v[222:223], v[220:221], s[90:91], v[232:233] op_sel_hi:[1,0,0]
	v_pk_fma_f32 v[228:229], v[226:227], s[90:91], v[232:233] op_sel_hi:[1,0,0]
	v_exp_f32_e32 v224, v224
	v_exp_f32_e32 v225, v225
	v_exp_f32_e32 v230, v230
	v_exp_f32_e32 v231, v231
	v_pk_fma_f32 v[222:223], v[220:221], v[222:223], s[94:95] op_sel_hi:[1,1,0]
	v_pk_fma_f32 v[228:229], v[226:227], v[228:229], s[94:95] op_sel_hi:[1,1,0]
	v_pk_fma_f32 v[222:223], v[220:221], v[222:223], s[96:97] op_sel_hi:[1,1,0]
	v_pk_fma_f32 v[228:229], v[226:227], v[228:229], s[96:97] op_sel_hi:[1,1,0]
	v_pk_fma_f32 v[222:223], v[220:221], v[222:223], s[98:99] op_sel_hi:[1,1,0]
	v_pk_fma_f32 v[228:229], v[226:227], v[228:229], s[98:99] op_sel_hi:[1,1,0]
	v_pk_mul_f32 v[222:223], v[220:221], v[222:223]
	v_pk_mul_f32 v[228:229], v[226:227], v[228:229]
	v_pk_mul_f32 v[222:223], v[224:225], v[222:223]
	v_pk_mul_f32 v[228:229], v[230:231], v[228:229]
	v_max_f32_e32 v220, 0, v160
	v_max_f32_e32 v221, 0, v161
	v_max_f32_e32 v226, 0, v166
	v_max_f32_e32 v227, 0, v167
	v_fma_f32 v160, -|v160|, v222, v220
	v_fma_f32 v161, -|v161|, v223, v221
	v_fma_f32 v166, -|v166|, v228, v226
	v_fma_f32 v167, -|v167|, v229, v227
.LBB0_136:
	s_nop 0
	v_cvt_pk_bf16_f32 v174, v164, v165
	v_cvt_pk_bf16_f32 v175, v162, v163
	v_cvt_pk_bf16_f32 v176, v160, v161
	v_cvt_pk_bf16_f32 v177, v166, v167
	v_pk_mul_f32 v[162:163], v[100:101], v[158:159] op_sel_hi:[1,0]
	v_pk_mul_f32 v[164:165], v[98:99], v[158:159] op_sel_hi:[1,0]
	v_pk_mul_f32 v[166:167], v[104:105], v[158:159] op_sel_hi:[1,0]
	s_and_b64 vcc, exec, s[6:7]
	v_pk_mul_f32 v[168:169], v[102:103], v[158:159] op_sel_hi:[1,0]
	global_store_dwordx4 v[156:157], v[174:177], off offset:64
	s_cbranch_vccnz .LBB0_138
; __device__ __forceinline__ unsigned pk_bf16(float lo, float hi) { f32x2 v = {lo, hi}; bf16x2_t b = __builtin_convertvector(v, bf16x2_t); return __builtin_bit_cast(unsigned, b); }
; __device__ __forceinline__ f32x4 gelu4(f32x4 v) { f32x2 a = gelu_pk((f32x2){v[0], v[1]}), b = gelu_pk((f32x2){v[2], v[3]}); return (f32x4){a.x, a.y, b.x, b.y}; }
; __device__ __forceinline__ f32x2 gelu_pk(f32x2 v) {
;     const f32x2 av = __builtin_elementwise_abs(v), d = av * 0.2316418882f + 1.0f;
;     f32x2 t; t.x = __builtin_amdgcn_rcpf(d.x); t.y = __builtin_amdgcn_rcpf(d.y);
;     f32x2 q = t * 0.5307027145f + (-0.7265760135f); q = q * t + 0.7107068705f; q = q * t + (-0.142248368f); q = q * t + 0.127414796f; q = q * t;
;     const f32x2 s = (v * v) * (-0.72134752044f);
;     f32x2 e; e.x = __builtin_amdgcn_exp2f(s.x); e.y = __builtin_amdgcn_exp2f(s.y);
;     const f32x2 m = v * (q * e), r = v - m;
;     f32x2 o; o.x = v.x < 0.f ? m.x : r.x; o.y = v.y < 0.f ? m.y : r.y; return o;
; }
;     __device__ __forceinline__ void operator()(const f32x4 (&acc)[2][2][4][2], const Unit& u, int wr, int wc, int fr, int fq, float rp0, float rp1, const f32x4& raw0, const f32x4& raw1, float& rn0, float& rn1) const {
;     ...
;                 for (int m = 0; m < 4; ++m) {
;                     const int roff = ai * HALF + m * 16; const float r = rs[m];
; #pragma unroll
;                     for (int bj = 0; bj < 2; ++bj) {
;                         f32x4 v0 = acc[ai][bj][m][0] * r, v1 = acc[ai][bj][m][1] * r;
;                         if (gel) { v0 = gelu4(v0); v1 = gelu4(v1); }
;                         u32x4 w; w.x = pk_bf16(v0[0], v0[1]); w.y = pk_bf16(v0[2], v0[3]); w.z = pk_bf16(v1[0], v1[1]); w.w = pk_bf16(v1[2], v1[3]);
;                         *(u32x4*)(base + (size_t)roff * ld + bj * 32) = w;
;                     }
	v_fma_f32 v220, |v164|, s88, 1.0
	v_fma_f32 v221, |v165|, s88, 1.0
	v_fma_f32 v226, |v162|, s88, 1.0
	v_fma_f32 v227, |v163|, s88, 1.0
	v_pk_mul_f32 v[224:225], v[164:165], v[164:165]
	v_pk_mul_f32 v[230:231], v[162:163], v[162:163]
	v_rcp_f32_e32 v220, v220
	v_rcp_f32_e32 v221, v221
	v_rcp_f32_e32 v226, v226
	v_rcp_f32_e32 v227, v227
	v_pk_mul_f32 v[224:225], v[224:225], s[72:73] op_sel_hi:[1,0]
	v_pk_mul_f32 v[230:231], v[230:231], s[72:73] op_sel_hi:[1,0]
	v_pk_fma_f32 v[222:223], v[220:221], s[90:91], v[232:233] op_sel_hi:[1,0,0]
	v_pk_fma_f32 v[228:229], v[226:227], s[90:91], v[232:233] op_sel_hi:[1,0,0]
	v_exp_f32_e32 v224, v224
	v_exp_f32_e32 v225, v225
	v_exp_f32_e32 v230, v230
	v_exp_f32_e32 v231, v231
	v_pk_fma_f32 v[222:223], v[220:221], v[222:223], s[94:95] op_sel_hi:[1,1,0]
	v_pk_fma_f32 v[228:229], v[226:227], v[228:229], s[94:95] op_sel_hi:[1,1,0]
	v_pk_fma_f32 v[222:223], v[220:221], v[222:223], s[96:97] op_sel_hi:[1,1,0]
	v_pk_fma_f32 v[228:229], v[226:227], v[228:229], s[96:97] op_sel_hi:[1,1,0]
	v_pk_fma_f32 v[222:223], v[220:221], v[222:223], s[98:99] op_sel_hi:[1,1,0]
	v_pk_fma_f32 v[228:229], v[226:227], v[228:229], s[98:99] op_sel_hi:[1,1,0]
	v_pk_mul_f32 v[222:223], v[220:221], v[222:223]
	v_pk_mul_f32 v[228:229], v[226:227], v[228:229]
	v_pk_mul_f32 v[222:223], v[224:225], v[222:223]
	v_pk_mul_f32 v[228:229], v[230:231], v[228:229]
	v_max_f32_e32 v220, 0, v164
	v_max_f32_e32 v221, 0, v165
	v_max_f32_e32 v226, 0, v162
	v_max_f32_e32 v227, 0, v163
	v_fma_f32 v164, -|v164|, v222, v220
	v_fma_f32 v165, -|v165|, v223, v221
	v_fma_f32 v162, -|v162|, v228, v226
	v_fma_f32 v163, -|v163|, v229, v227
	v_fma_f32 v220, |v168|, s88, 1.0
	v_fma_f32 v221, |v169|, s88, 1.0
	v_fma_f32 v226, |v166|, s88, 1.0
	v_fma_f32 v227, |v167|, s88, 1.0
	v_pk_mul_f32 v[224:225], v[168:169], v[168:169]
	v_pk_mul_f32 v[230:231], v[166:167], v[166:167]
	v_rcp_f32_e32 v220, v220
	v_rcp_f32_e32 v221, v221
	v_rcp_f32_e32 v226, v226
	v_rcp_f32_e32 v227, v227
	v_pk_mul_f32 v[224:225], v[224:225], s[72:73] op_sel_hi:[1,0]
	v_pk_mul_f32 v[230:231], v[230:231], s[72:73] op_sel_hi:[1,0]
	v_pk_fma_f32 v[222:223], v[220:221], s[90:91], v[232:233] op_sel_hi:[1,0,0]
	v_pk_fma_f32 v[228:229], v[226:227], s[90:91], v[232:233] op_sel_hi:[1,0,0]
	v_exp_f32_e32 v224, v224
	v_exp_f32_e32 v225, v225
	v_exp_f32_e32 v230, v230
	v_exp_f32_e32 v231, v231
	v_pk_fma_f32 v[222:223], v[220:221], v[222:223], s[94:95] op_sel_hi:[1,1,0]
	v_pk_fma_f32 v[228:229], v[226:227], v[228:229], s[94:95] op_sel_hi:[1,1,0]
	v_pk_fma_f32 v[222:223], v[220:221], v[222:223], s[96:97] op_sel_hi:[1,1,0]
	v_pk_fma_f32 v[228:229], v[226:227], v[228:229], s[96:97] op_sel_hi:[1,1,0]
	v_pk_fma_f32 v[222:223], v[220:221], v[222:223], s[98:99] op_sel_hi:[1,1,0]
	v_pk_fma_f32 v[228:229], v[226:227], v[228:229], s[98:99] op_sel_hi:[1,1,0]
	v_pk_mul_f32 v[222:223], v[220:221], v[222:223]
	v_pk_mul_f32 v[228:229], v[226:227], v[228:229]
	v_pk_mul_f32 v[222:223], v[224:225], v[222:223]
	v_pk_mul_f32 v[228:229], v[230:231], v[228:229]
	v_max_f32_e32 v220, 0, v168
	v_max_f32_e32 v221, 0, v169
	v_max_f32_e32 v226, 0, v166
	v_max_f32_e32 v227, 0, v167
	v_fma_f32 v168, -|v168|, v222, v220
	v_fma_f32 v169, -|v169|, v223, v221
	v_fma_f32 v166, -|v166|, v228, v226
	v_fma_f32 v167, -|v167|, v229, v227
.LBB0_138:
	v_mov_b32_e32 v159, v158
	s_lshl_b32 s76, s10, 5
	v_cvt_pk_bf16_f32 v177, v166, v167
	v_mov_b32_e32 v166, v158
	v_mov_b32_e32 v167, v158
	v_lshl_add_u64 v[160:161], v[156:157], 0, s[76:77]
	v_cvt_pk_bf16_f32 v174, v164, v165
	v_cvt_pk_bf16_f32 v175, v162, v163
	v_cvt_pk_bf16_f32 v176, v168, v169
	v_pk_mul_f32 v[162:163], v[108:109], v[166:167]
	v_pk_mul_f32 v[164:165], v[106:107], v[158:159]
	v_pk_mul_f32 v[166:167], v[112:113], v[166:167]
	s_and_b64 vcc, exec, s[6:7]
	v_pk_mul_f32 v[158:159], v[110:111], v[158:159]
	global_store_dwordx4 v[160:161], v[174:177], off
	s_cbranch_vccnz .LBB0_140
	v_fma_f32 v220, |v164|, s88, 1.0
	v_fma_f32 v221, |v165|, s88, 1.0
	v_fma_f32 v226, |v162|, s88, 1.0
	v_fma_f32 v227, |v163|, s88, 1.0
	v_pk_mul_f32 v[224:225], v[164:165], v[164:165]
	v_pk_mul_f32 v[230:231], v[162:163], v[162:163]
	v_rcp_f32_e32 v220, v220
	v_rcp_f32_e32 v221, v221
	v_rcp_f32_e32 v226, v226
	v_rcp_f32_e32 v227, v227
	v_pk_mul_f32 v[224:225], v[224:225], s[72:73] op_sel_hi:[1,0]
	v_pk_mul_f32 v[230:231], v[230:231], s[72:73] op_sel_hi:[1,0]
	v_pk_fma_f32 v[222:223], v[220:221], s[90:91], v[232:233] op_sel_hi:[1,0,0]
	v_pk_fma_f32 v[228:229], v[226:227], s[90:91], v[232:233] op_sel_hi:[1,0,0]
	v_exp_f32_e32 v224, v224
	v_exp_f32_e32 v225, v225
	v_exp_f32_e32 v230, v230
	v_exp_f32_e32 v231, v231
	v_pk_fma_f32 v[222:223], v[220:221], v[222:223], s[94:95] op_sel_hi:[1,1,0]
	v_pk_fma_f32 v[228:229], v[226:227], v[228:229], s[94:95] op_sel_hi:[1,1,0]
	v_pk_fma_f32 v[222:223], v[220:221], v[222:223], s[96:97] op_sel_hi:[1,1,0]
	v_pk_fma_f32 v[228:229], v[226:227], v[228:229], s[96:97] op_sel_hi:[1,1,0]
	v_pk_fma_f32 v[222:223], v[220:221], v[222:223], s[98:99] op_sel_hi:[1,1,0]
	v_pk_fma_f32 v[228:229], v[226:227], v[228:229], s[98:99] op_sel_hi:[1,1,0]
	v_pk_mul_f32 v[222:223], v[220:221], v[222:223]
	v_pk_mul_f32 v[228:229], v[226:227], v[228:229]
	v_pk_mul_f32 v[222:223], v[224:225], v[222:223]
	v_pk_mul_f32 v[228:229], v[230:231], v[228:229]
	v_max_f32_e32 v220, 0, v164
	v_max_f32_e32 v221, 0, v165
	v_max_f32_e32 v226, 0, v162
	v_max_f32_e32 v227, 0, v163
	v_fma_f32 v164, -|v164|, v222, v220
	v_fma_f32 v165, -|v165|, v223, v221
	v_fma_f32 v162, -|v162|, v228, v226
	v_fma_f32 v163, -|v163|, v229, v227
	v_fma_f32 v220, |v158|, s88, 1.0
	v_fma_f32 v221, |v159|, s88, 1.0
	v_fma_f32 v226, |v166|, s88, 1.0
; __device__ __forceinline__ unsigned pk_bf16(float lo, float hi) { f32x2 v = {lo, hi}; bf16x2_t b = __builtin_convertvector(v, bf16x2_t); return __builtin_bit_cast(unsigned, b); }
; __device__ __forceinline__ f32x4 gelu4(f32x4 v) { f32x2 a = gelu_pk((f32x2){v[0], v[1]}), b = gelu_pk((f32x2){v[2], v[3]}); return (f32x4){a.x, a.y, b.x, b.y}; }
; __device__ __forceinline__ f32x2 gelu_pk(f32x2 v) {
;     const f32x2 av = __builtin_elementwise_abs(v), d = av * 0.2316418882f + 1.0f;
;     f32x2 t; t.x = __builtin_amdgcn_rcpf(d.x); t.y = __builtin_amdgcn_rcpf(d.y);
;     f32x2 q = t * 0.5307027145f + (-0.7265760135f); q = q * t + 0.7107068705f; q = q * t + (-0.142248368f); q = q * t + 0.127414796f; q = q * t;
;     const f32x2 s = (v * v) * (-0.72134752044f);
;     f32x2 e; e.x = __builtin_amdgcn_exp2f(s.x); e.y = __builtin_amdgcn_exp2f(s.y);
;     const f32x2 m = v * (q * e), r = v - m;
;     f32x2 o; o.x = v.x < 0.f ? m.x : r.x; o.y = v.y < 0.f ? m.y : r.y; return o;
; }
;     __device__ __forceinline__ void operator()(const f32x4 (&acc)[2][2][4][2], const Unit& u, int wr, int wc, int fr, int fq, float rp0, float rp1, const f32x4& raw0, const f32x4& raw1, float& rn0, float& rn1) const {
;     ...
;                 for (int m = 0; m < 4; ++m) {
;                     const int roff = ai * HALF + m * 16; const float r = rs[m];
; #pragma unroll
;                     for (int bj = 0; bj < 2; ++bj) {
;                         f32x4 v0 = acc[ai][bj][m][0] * r, v1 = acc[ai][bj][m][1] * r;
;                         if (gel) { v0 = gelu4(v0); v1 = gelu4(v1); }
;                         u32x4 w; w.x = pk_bf16(v0[0], v0[1]); w.y = pk_bf16(v0[2], v0[3]); w.z = pk_bf16(v1[0], v1[1]); w.w = pk_bf16(v1[2], v1[3]);
;                         *(u32x4*)(base + (size_t)roff * ld + bj * 32) = w;
;                     }
	v_fma_f32 v227, |v167|, s88, 1.0
	v_pk_mul_f32 v[224:225], v[158:159], v[158:159]
	v_pk_mul_f32 v[230:231], v[166:167], v[166:167]
	v_rcp_f32_e32 v220, v220
	v_rcp_f32_e32 v221, v221
	v_rcp_f32_e32 v226, v226
	v_rcp_f32_e32 v227, v227
	v_pk_mul_f32 v[224:225], v[224:225], s[72:73] op_sel_hi:[1,0]
	v_pk_mul_f32 v[230:231], v[230:231], s[72:73] op_sel_hi:[1,0]
	v_pk_fma_f32 v[222:223], v[220:221], s[90:91], v[232:233] op_sel_hi:[1,0,0]
	v_pk_fma_f32 v[228:229], v[226:227], s[90:91], v[232:233] op_sel_hi:[1,0,0]
	v_exp_f32_e32 v224, v224
	v_exp_f32_e32 v225, v225
	v_exp_f32_e32 v230, v230
	v_exp_f32_e32 v231, v231
	v_pk_fma_f32 v[222:223], v[220:221], v[222:223], s[94:95] op_sel_hi:[1,1,0]
	v_pk_fma_f32 v[228:229], v[226:227], v[228:229], s[94:95] op_sel_hi:[1,1,0]
	v_pk_fma_f32 v[222:223], v[220:221], v[222:223], s[96:97] op_sel_hi:[1,1,0]
	v_pk_fma_f32 v[228:229], v[226:227], v[228:229], s[96:97] op_sel_hi:[1,1,0]
	v_pk_fma_f32 v[222:223], v[220:221], v[222:223], s[98:99] op_sel_hi:[1,1,0]
	v_pk_fma_f32 v[228:229], v[226:227], v[228:229], s[98:99] op_sel_hi:[1,1,0]
	v_pk_mul_f32 v[222:223], v[220:221], v[222:223]
	v_pk_mul_f32 v[228:229], v[226:227], v[228:229]
	v_pk_mul_f32 v[222:223], v[224:225], v[222:223]
	v_pk_mul_f32 v[228:229], v[230:231], v[228:229]
	v_max_f32_e32 v220, 0, v158
	v_max_f32_e32 v221, 0, v159
	v_max_f32_e32 v226, 0, v166
	v_max_f32_e32 v227, 0, v167
	v_fma_f32 v158, -|v158|, v222, v220
	v_fma_f32 v159, -|v159|, v223, v221
	v_fma_f32 v166, -|v166|, v228, v226
	v_fma_f32 v167, -|v167|, v229, v227
.LBB0_140:
	s_nop 0
	v_cvt_pk_bf16_f32 v174, v164, v165
	v_cvt_pk_bf16_f32 v175, v162, v163
	v_cvt_pk_bf16_f32 v176, v158, v159
	v_cvt_pk_bf16_f32 v177, v166, v167
	v_pk_mul_f32 v[162:163], v[76:77], v[140:141] op_sel_hi:[1,0]
	v_pk_mul_f32 v[164:165], v[74:75], v[140:141] op_sel_hi:[1,0]
	v_pk_mul_f32 v[166:167], v[80:81], v[140:141] op_sel_hi:[1,0]
	s_and_b64 vcc, exec, s[6:7]
	v_pk_mul_f32 v[168:169], v[78:79], v[140:141] op_sel_hi:[1,0]
	global_store_dwordx4 v[160:161], v[174:177], off offset:64
	s_cbranch_vccnz .LBB0_142
	v_fma_f32 v220, |v164|, s88, 1.0
	v_fma_f32 v221, |v165|, s88, 1.0
	v_fma_f32 v226, |v162|, s88, 1.0
	v_fma_f32 v227, |v163|, s88, 1.0
	v_pk_mul_f32 v[224:225], v[164:165], v[164:165]
	v_pk_mul_f32 v[230:231], v[162:163], v[162:163]
	v_rcp_f32_e32 v220, v220
	v_rcp_f32_e32 v221, v221
	v_rcp_f32_e32 v226, v226
	v_rcp_f32_e32 v227, v227
	v_pk_mul_f32 v[224:225], v[224:225], s[72:73] op_sel_hi:[1,0]
	v_pk_mul_f32 v[230:231], v[230:231], s[72:73] op_sel_hi:[1,0]
	v_pk_fma_f32 v[222:223], v[220:221], s[90:91], v[232:233] op_sel_hi:[1,0,0]
	v_pk_fma_f32 v[228:229], v[226:227], s[90:91], v[232:233] op_sel_hi:[1,0,0]
	v_exp_f32_e32 v224, v224
	v_exp_f32_e32 v225, v225
	v_exp_f32_e32 v230, v230
	v_exp_f32_e32 v231, v231
	v_pk_fma_f32 v[222:223], v[220:221], v[222:223], s[94:95] op_sel_hi:[1,1,0]
	v_pk_fma_f32 v[228:229], v[226:227], v[228:229], s[94:95] op_sel_hi:[1,1,0]
	v_pk_fma_f32 v[222:223], v[220:221], v[222:223], s[96:97] op_sel_hi:[1,1,0]
	v_pk_fma_f32 v[228:229], v[226:227], v[228:229], s[96:97] op_sel_hi:[1,1,0]
	v_pk_fma_f32 v[222:223], v[220:221], v[222:223], s[98:99] op_sel_hi:[1,1,0]
	v_pk_fma_f32 v[228:229], v[226:227], v[228:229], s[98:99] op_sel_hi:[1,1,0]
	v_pk_mul_f32 v[222:223], v[220:221], v[222:223]
	v_pk_mul_f32 v[228:229], v[226:227], v[228:229]
	v_pk_mul_f32 v[222:223], v[224:225], v[222:223]
	v_pk_mul_f32 v[228:229], v[230:231], v[228:229]
	v_max_f32_e32 v220, 0, v164
	v_max_f32_e32 v221, 0, v165
	v_max_f32_e32 v226, 0, v162
	v_max_f32_e32 v227, 0, v163
	v_fma_f32 v164, -|v164|, v222, v220
	v_fma_f32 v165, -|v165|, v223, v221
	v_fma_f32 v162, -|v162|, v228, v226
	v_fma_f32 v163, -|v163|, v229, v227
	v_fma_f32 v220, |v168|, s88, 1.0
	v_fma_f32 v221, |v169|, s88, 1.0
	v_fma_f32 v226, |v166|, s88, 1.0
	v_fma_f32 v227, |v167|, s88, 1.0
	v_pk_mul_f32 v[224:225], v[168:169], v[168:169]
	v_pk_mul_f32 v[230:231], v[166:167], v[166:167]
	v_rcp_f32_e32 v220, v220
	v_rcp_f32_e32 v221, v221
	v_rcp_f32_e32 v226, v226
	v_rcp_f32_e32 v227, v227
	v_pk_mul_f32 v[224:225], v[224:225], s[72:73] op_sel_hi:[1,0]
	v_pk_mul_f32 v[230:231], v[230:231], s[72:73] op_sel_hi:[1,0]
	v_pk_fma_f32 v[222:223], v[220:221], s[90:91], v[232:233] op_sel_hi:[1,0,0]
	v_pk_fma_f32 v[228:229], v[226:227], s[90:91], v[232:233] op_sel_hi:[1,0,0]
	v_exp_f32_e32 v224, v224
	v_exp_f32_e32 v225, v225
	v_exp_f32_e32 v230, v230
	v_exp_f32_e32 v231, v231
	v_pk_fma_f32 v[222:223], v[220:221], v[222:223], s[94:95] op_sel_hi:[1,1,0]
	v_pk_fma_f32 v[228:229], v[226:227], v[228:229], s[94:95] op_sel_hi:[1,1,0]
	v_pk_fma_f32 v[222:223], v[220:221], v[222:223], s[96:97] op_sel_hi:[1,1,0]
	v_pk_fma_f32 v[228:229], v[226:227], v[228:229], s[96:97] op_sel_hi:[1,1,0]
	v_pk_fma_f32 v[222:223], v[220:221], v[222:223], s[98:99] op_sel_hi:[1,1,0]
	v_pk_fma_f32 v[228:229], v[226:227], v[228:229], s[98:99] op_sel_hi:[1,1,0]
	v_pk_mul_f32 v[222:223], v[220:221], v[222:223]
	v_pk_mul_f32 v[228:229], v[226:227], v[228:229]
	v_pk_mul_f32 v[222:223], v[224:225], v[222:223]
	v_pk_mul_f32 v[228:229], v[230:231], v[228:229]
	v_max_f32_e32 v220, 0, v168
	v_max_f32_e32 v221, 0, v169
	v_max_f32_e32 v226, 0, v166
	v_max_f32_e32 v227, 0, v167
	v_fma_f32 v168, -|v168|, v222, v220
	v_fma_f32 v169, -|v169|, v223, v221
	v_fma_f32 v166, -|v166|, v228, v226
	v_fma_f32 v167, -|v167|, v229, v227
; __device__ __forceinline__ unsigned pk_bf16(float lo, float hi) { f32x2 v = {lo, hi}; bf16x2_t b = __builtin_convertvector(v, bf16x2_t); return __builtin_bit_cast(unsigned, b); }
; __device__ __forceinline__ f32x4 gelu4(f32x4 v) { f32x2 a = gelu_pk((f32x2){v[0], v[1]}), b = gelu_pk((f32x2){v[2], v[3]}); return (f32x4){a.x, a.y, b.x, b.y}; }
; __device__ __forceinline__ f32x2 gelu_pk(f32x2 v) {
;     const f32x2 av = __builtin_elementwise_abs(v), d = av * 0.2316418882f + 1.0f;
;     f32x2 t; t.x = __builtin_amdgcn_rcpf(d.x); t.y = __builtin_amdgcn_rcpf(d.y);
;     f32x2 q = t * 0.5307027145f + (-0.7265760135f); q = q * t + 0.7107068705f; q = q * t + (-0.142248368f); q = q * t + 0.127414796f; q = q * t;
;     const f32x2 s = (v * v) * (-0.72134752044f);
;     f32x2 e; e.x = __builtin_amdgcn_exp2f(s.x); e.y = __builtin_amdgcn_exp2f(s.y);
;     const f32x2 m = v * (q * e), r = v - m;
;     f32x2 o; o.x = v.x < 0.f ? m.x : r.x; o.y = v.y < 0.f ? m.y : r.y; return o;
; }
;     __device__ __forceinline__ void operator()(const f32x4 (&acc)[2][2][4][2], const Unit& u, int wr, int wc, int fr, int fq, float rp0, float rp1, const f32x4& raw0, const f32x4& raw1, float& rn0, float& rn1) const {
;     ...
;                 for (int m = 0; m < 4; ++m) {
;                     const int roff = ai * HALF + m * 16; const float r = rs[m];
; #pragma unroll
;                     for (int bj = 0; bj < 2; ++bj) {
;                         f32x4 v0 = acc[ai][bj][m][0] * r, v1 = acc[ai][bj][m][1] * r;
;                         if (gel) { v0 = gelu4(v0); v1 = gelu4(v1); }
;                         u32x4 w; w.x = pk_bf16(v0[0], v0[1]); w.y = pk_bf16(v0[2], v0[3]); w.z = pk_bf16(v1[0], v1[1]); w.w = pk_bf16(v1[2], v1[3]);
;                         *(u32x4*)(base + (size_t)roff * ld + bj * 32) = w;
;                     }
.LBB0_142:
	v_mov_b32_e32 v141, v140
	v_lshl_add_u64 v[158:159], v[160:161], 0, s[76:77]
	v_cvt_pk_bf16_f32 v160, v164, v165
	v_cvt_pk_bf16_f32 v161, v162, v163
	v_cvt_pk_bf16_f32 v162, v168, v169
	v_cvt_pk_bf16_f32 v163, v166, v167
	v_mov_b32_e32 v164, v140
	v_mov_b32_e32 v165, v140
	global_store_dwordx4 v[158:159], v[160:163], off
	s_and_b64 vcc, exec, s[6:7]
	s_nop 0
	v_pk_mul_f32 v[160:161], v[92:93], v[164:165]
	v_pk_mul_f32 v[162:163], v[90:91], v[140:141]
	v_pk_mul_f32 v[164:165], v[96:97], v[164:165]
	v_pk_mul_f32 v[140:141], v[94:95], v[140:141]
	s_cbranch_vccnz .LBB0_144
	v_fma_f32 v220, |v162|, s88, 1.0
	v_fma_f32 v221, |v163|, s88, 1.0
	v_fma_f32 v226, |v160|, s88, 1.0
	v_fma_f32 v227, |v161|, s88, 1.0
	v_pk_mul_f32 v[224:225], v[162:163], v[162:163]
	v_pk_mul_f32 v[230:231], v[160:161], v[160:161]
	v_rcp_f32_e32 v220, v220
	v_rcp_f32_e32 v221, v221
	v_rcp_f32_e32 v226, v226
	v_rcp_f32_e32 v227, v227
	v_pk_mul_f32 v[224:225], v[224:225], s[72:73] op_sel_hi:[1,0]
	v_pk_mul_f32 v[230:231], v[230:231], s[72:73] op_sel_hi:[1,0]
	v_pk_fma_f32 v[222:223], v[220:221], s[90:91], v[232:233] op_sel_hi:[1,0,0]
	v_pk_fma_f32 v[228:229], v[226:227], s[90:91], v[232:233] op_sel_hi:[1,0,0]
	v_exp_f32_e32 v224, v224
	v_exp_f32_e32 v225, v225
	v_exp_f32_e32 v230, v230
	v_exp_f32_e32 v231, v231
	v_pk_fma_f32 v[222:223], v[220:221], v[222:223], s[94:95] op_sel_hi:[1,1,0]
	v_pk_fma_f32 v[228:229], v[226:227], v[228:229], s[94:95] op_sel_hi:[1,1,0]
	v_pk_fma_f32 v[222:223], v[220:221], v[222:223], s[96:97] op_sel_hi:[1,1,0]
	v_pk_fma_f32 v[228:229], v[226:227], v[228:229], s[96:97] op_sel_hi:[1,1,0]
	v_pk_fma_f32 v[222:223], v[220:221], v[222:223], s[98:99] op_sel_hi:[1,1,0]
	v_pk_fma_f32 v[228:229], v[226:227], v[228:229], s[98:99] op_sel_hi:[1,1,0]
	v_pk_mul_f32 v[222:223], v[220:221], v[222:223]
	v_pk_mul_f32 v[228:229], v[226:227], v[228:229]
	v_pk_mul_f32 v[222:223], v[224:225], v[222:223]
	v_pk_mul_f32 v[228:229], v[230:231], v[228:229]
	v_max_f32_e32 v220, 0, v162
	v_max_f32_e32 v221, 0, v163
	v_max_f32_e32 v226, 0, v160
	v_max_f32_e32 v227, 0, v161
	v_fma_f32 v162, -|v162|, v222, v220
	v_fma_f32 v163, -|v163|, v223, v221
	v_fma_f32 v160, -|v160|, v228, v226
	v_fma_f32 v161, -|v161|, v229, v227
	v_fma_f32 v220, |v140|, s88, 1.0
	v_fma_f32 v221, |v141|, s88, 1.0
	v_fma_f32 v226, |v164|, s88, 1.0
	v_fma_f32 v227, |v165|, s88, 1.0
	v_pk_mul_f32 v[224:225], v[140:141], v[140:141]
	v_pk_mul_f32 v[230:231], v[164:165], v[164:165]
	v_rcp_f32_e32 v220, v220
	v_rcp_f32_e32 v221, v221
	v_rcp_f32_e32 v226, v226
	v_rcp_f32_e32 v227, v227
	v_pk_mul_f32 v[224:225], v[224:225], s[72:73] op_sel_hi:[1,0]
	v_pk_mul_f32 v[230:231], v[230:231], s[72:73] op_sel_hi:[1,0]
	v_pk_fma_f32 v[222:223], v[220:221], s[90:91], v[232:233] op_sel_hi:[1,0,0]
	v_pk_fma_f32 v[228:229], v[226:227], s[90:91], v[232:233] op_sel_hi:[1,0,0]
	v_exp_f32_e32 v224, v224
	v_exp_f32_e32 v225, v225
	v_exp_f32_e32 v230, v230
	v_exp_f32_e32 v231, v231
	v_pk_fma_f32 v[222:223], v[220:221], v[222:223], s[94:95] op_sel_hi:[1,1,0]
	v_pk_fma_f32 v[228:229], v[226:227], v[228:229], s[94:95] op_sel_hi:[1,1,0]
	v_pk_fma_f32 v[222:223], v[220:221], v[222:223], s[96:97] op_sel_hi:[1,1,0]
	v_pk_fma_f32 v[228:229], v[226:227], v[228:229], s[96:97] op_sel_hi:[1,1,0]
	v_pk_fma_f32 v[222:223], v[220:221], v[222:223], s[98:99] op_sel_hi:[1,1,0]
	v_pk_fma_f32 v[228:229], v[226:227], v[228:229], s[98:99] op_sel_hi:[1,1,0]
	v_pk_mul_f32 v[222:223], v[220:221], v[222:223]
	v_pk_mul_f32 v[228:229], v[226:227], v[228:229]
	v_pk_mul_f32 v[222:223], v[224:225], v[222:223]
	v_pk_mul_f32 v[228:229], v[230:231], v[228:229]
	v_max_f32_e32 v220, 0, v140
	v_max_f32_e32 v221, 0, v141
	v_max_f32_e32 v226, 0, v164
	v_max_f32_e32 v227, 0, v165
	v_fma_f32 v140, -|v140|, v222, v220
	v_fma_f32 v141, -|v141|, v223, v221
	v_fma_f32 v164, -|v164|, v228, v226
	v_fma_f32 v165, -|v165|, v229, v227
.LBB0_144:
	v_cvt_pk_bf16_f32 v166, v162, v163
	v_cvt_pk_bf16_f32 v167, v160, v161
	v_cvt_pk_bf16_f32 v168, v140, v141
	v_cvt_pk_bf16_f32 v169, v164, v165
	global_store_dwordx4 v[158:159], v[166:169], off offset:64
	v_pk_mul_f32 v[140:141], v[68:69], v[138:139] op_sel_hi:[1,0]
	v_pk_mul_f32 v[162:163], v[66:67], v[138:139] op_sel_hi:[1,0]
	v_pk_mul_f32 v[164:165], v[72:73], v[138:139] op_sel_hi:[1,0]
	s_and_b64 vcc, exec, s[6:7]
	v_pk_mul_f32 v[166:167], v[70:71], v[138:139] op_sel_hi:[1,0]
	s_cbranch_vccnz .LBB0_146
; __device__ __forceinline__ unsigned pk_bf16(float lo, float hi) { f32x2 v = {lo, hi}; bf16x2_t b = __builtin_convertvector(v, bf16x2_t); return __builtin_bit_cast(unsigned, b); }
; __device__ __forceinline__ f32x4 gelu4(f32x4 v) { f32x2 a = gelu_pk((f32x2){v[0], v[1]}), b = gelu_pk((f32x2){v[2], v[3]}); return (f32x4){a.x, a.y, b.x, b.y}; }
; __device__ __forceinline__ f32x2 gelu_pk(f32x2 v) {
;     const f32x2 av = __builtin_elementwise_abs(v), d = av * 0.2316418882f + 1.0f;
;     f32x2 t; t.x = __builtin_amdgcn_rcpf(d.x); t.y = __builtin_amdgcn_rcpf(d.y);
;     f32x2 q = t * 0.5307027145f + (-0.7265760135f); q = q * t + 0.7107068705f; q = q * t + (-0.142248368f); q = q * t + 0.127414796f; q = q * t;
;     const f32x2 s = (v * v) * (-0.72134752044f);
;     f32x2 e; e.x = __builtin_amdgcn_exp2f(s.x); e.y = __builtin_amdgcn_exp2f(s.y);
;     const f32x2 m = v * (q * e), r = v - m;
;     f32x2 o; o.x = v.x < 0.f ? m.x : r.x; o.y = v.y < 0.f ? m.y : r.y; return o;
; }
;     __device__ __forceinline__ void operator()(const f32x4 (&acc)[2][2][4][2], const Unit& u, int wr, int wc, int fr, int fq, float rp0, float rp1, const f32x4& raw0, const f32x4& raw1, float& rn0, float& rn1) const {
;     ...
;                 for (int m = 0; m < 4; ++m) {
;                     const int roff = ai * HALF + m * 16; const float r = rs[m];
; #pragma unroll
;                     for (int bj = 0; bj < 2; ++bj) {
;                         f32x4 v0 = acc[ai][bj][m][0] * r, v1 = acc[ai][bj][m][1] * r;
;                         if (gel) { v0 = gelu4(v0); v1 = gelu4(v1); }
;                         u32x4 w; w.x = pk_bf16(v0[0], v0[1]); w.y = pk_bf16(v0[2], v0[3]); w.z = pk_bf16(v1[0], v1[1]); w.w = pk_bf16(v1[2], v1[3]);
;                         *(u32x4*)(base + (size_t)roff * ld + bj * 32) = w;
;                     }
	v_fma_f32 v220, |v162|, s88, 1.0
	v_fma_f32 v221, |v163|, s88, 1.0
	v_fma_f32 v226, |v140|, s88, 1.0
	v_fma_f32 v227, |v141|, s88, 1.0
	v_pk_mul_f32 v[224:225], v[162:163], v[162:163]
	v_pk_mul_f32 v[230:231], v[140:141], v[140:141]
	v_rcp_f32_e32 v220, v220
	v_rcp_f32_e32 v221, v221
	v_rcp_f32_e32 v226, v226
	v_rcp_f32_e32 v227, v227
	v_pk_mul_f32 v[224:225], v[224:225], s[72:73] op_sel_hi:[1,0]
	v_pk_mul_f32 v[230:231], v[230:231], s[72:73] op_sel_hi:[1,0]
	v_pk_fma_f32 v[222:223], v[220:221], s[90:91], v[232:233] op_sel_hi:[1,0,0]
	v_pk_fma_f32 v[228:229], v[226:227], s[90:91], v[232:233] op_sel_hi:[1,0,0]
	v_exp_f32_e32 v224, v224
	v_exp_f32_e32 v225, v225
	v_exp_f32_e32 v230, v230
	v_exp_f32_e32 v231, v231
	v_pk_fma_f32 v[222:223], v[220:221], v[222:223], s[94:95] op_sel_hi:[1,1,0]
	v_pk_fma_f32 v[228:229], v[226:227], v[228:229], s[94:95] op_sel_hi:[1,1,0]
	v_pk_fma_f32 v[222:223], v[220:221], v[222:223], s[96:97] op_sel_hi:[1,1,0]
	v_pk_fma_f32 v[228:229], v[226:227], v[228:229], s[96:97] op_sel_hi:[1,1,0]
	v_pk_fma_f32 v[222:223], v[220:221], v[222:223], s[98:99] op_sel_hi:[1,1,0]
	v_pk_fma_f32 v[228:229], v[226:227], v[228:229], s[98:99] op_sel_hi:[1,1,0]
	v_pk_mul_f32 v[222:223], v[220:221], v[222:223]
	v_pk_mul_f32 v[228:229], v[226:227], v[228:229]
	v_pk_mul_f32 v[222:223], v[224:225], v[222:223]
	v_pk_mul_f32 v[228:229], v[230:231], v[228:229]
	v_max_f32_e32 v220, 0, v162
	v_max_f32_e32 v221, 0, v163
	v_max_f32_e32 v226, 0, v140
	v_max_f32_e32 v227, 0, v141
	v_fma_f32 v162, -|v162|, v222, v220
	v_fma_f32 v163, -|v163|, v223, v221
	v_fma_f32 v140, -|v140|, v228, v226
	v_fma_f32 v141, -|v141|, v229, v227
	v_fma_f32 v220, |v166|, s88, 1.0
	v_fma_f32 v221, |v167|, s88, 1.0
	v_fma_f32 v226, |v164|, s88, 1.0
	v_fma_f32 v227, |v165|, s88, 1.0
	v_pk_mul_f32 v[224:225], v[166:167], v[166:167]
	v_pk_mul_f32 v[230:231], v[164:165], v[164:165]
	v_rcp_f32_e32 v220, v220
	v_rcp_f32_e32 v221, v221
	v_rcp_f32_e32 v226, v226
	v_rcp_f32_e32 v227, v227
	v_pk_mul_f32 v[224:225], v[224:225], s[72:73] op_sel_hi:[1,0]
	v_pk_mul_f32 v[230:231], v[230:231], s[72:73] op_sel_hi:[1,0]
	v_pk_fma_f32 v[222:223], v[220:221], s[90:91], v[232:233] op_sel_hi:[1,0,0]
	v_pk_fma_f32 v[228:229], v[226:227], s[90:91], v[232:233] op_sel_hi:[1,0,0]
	v_exp_f32_e32 v224, v224
	v_exp_f32_e32 v225, v225
	v_exp_f32_e32 v230, v230
	v_exp_f32_e32 v231, v231
	v_pk_fma_f32 v[222:223], v[220:221], v[222:223], s[94:95] op_sel_hi:[1,1,0]
	v_pk_fma_f32 v[228:229], v[226:227], v[228:229], s[94:95] op_sel_hi:[1,1,0]
	v_pk_fma_f32 v[222:223], v[220:221], v[222:223], s[96:97] op_sel_hi:[1,1,0]
	v_pk_fma_f32 v[228:229], v[226:227], v[228:229], s[96:97] op_sel_hi:[1,1,0]
	v_pk_fma_f32 v[222:223], v[220:221], v[222:223], s[98:99] op_sel_hi:[1,1,0]
	v_pk_fma_f32 v[228:229], v[226:227], v[228:229], s[98:99] op_sel_hi:[1,1,0]
	v_pk_mul_f32 v[222:223], v[220:221], v[222:223]
	v_pk_mul_f32 v[228:229], v[226:227], v[228:229]
	v_pk_mul_f32 v[222:223], v[224:225], v[222:223]
	v_pk_mul_f32 v[228:229], v[230:231], v[228:229]
	v_max_f32_e32 v220, 0, v166
	v_max_f32_e32 v221, 0, v167
	v_max_f32_e32 v226, 0, v164
	v_max_f32_e32 v227, 0, v165
	v_fma_f32 v166, -|v166|, v222, v220
	v_fma_f32 v167, -|v167|, v223, v221
	v_fma_f32 v164, -|v164|, v228, v226
	v_fma_f32 v165, -|v165|, v229, v227
.LBB0_146:
	v_mov_b32_e32 v139, v138
	v_cvt_pk_bf16_f32 v174, v162, v163
	v_mov_b32_e32 v162, v138
	v_mov_b32_e32 v163, v138
	v_lshl_add_u64 v[160:161], v[158:159], 0, s[76:77]
	v_cvt_pk_bf16_f32 v175, v140, v141
	v_cvt_pk_bf16_f32 v176, v166, v167
	v_cvt_pk_bf16_f32 v177, v164, v165
	v_pk_mul_f32 v[140:141], v[84:85], v[162:163]
	v_pk_mul_f32 v[158:159], v[82:83], v[138:139]
	v_pk_mul_f32 v[162:163], v[88:89], v[162:163]
	s_and_b64 vcc, exec, s[6:7]
	v_pk_mul_f32 v[138:139], v[86:87], v[138:139]
	global_store_dwordx4 v[160:161], v[174:177], off
	s_cbranch_vccnz .LBB0_148
	v_fma_f32 v220, |v158|, s88, 1.0
	v_fma_f32 v221, |v159|, s88, 1.0
	v_fma_f32 v226, |v140|, s88, 1.0
	v_fma_f32 v227, |v141|, s88, 1.0
	v_pk_mul_f32 v[224:225], v[158:159], v[158:159]
	v_pk_mul_f32 v[230:231], v[140:141], v[140:141]
	v_rcp_f32_e32 v220, v220
	v_rcp_f32_e32 v221, v221
	v_rcp_f32_e32 v226, v226
	v_rcp_f32_e32 v227, v227
	v_pk_mul_f32 v[224:225], v[224:225], s[72:73] op_sel_hi:[1,0]
	v_pk_mul_f32 v[230:231], v[230:231], s[72:73] op_sel_hi:[1,0]
	v_pk_fma_f32 v[222:223], v[220:221], s[90:91], v[232:233] op_sel_hi:[1,0,0]
	v_pk_fma_f32 v[228:229], v[226:227], s[90:91], v[232:233] op_sel_hi:[1,0,0]
	v_exp_f32_e32 v224, v224
	v_exp_f32_e32 v225, v225
	v_exp_f32_e32 v230, v230
	v_exp_f32_e32 v231, v231
	v_pk_fma_f32 v[222:223], v[220:221], v[222:223], s[94:95] op_sel_hi:[1,1,0]
	v_pk_fma_f32 v[228:229], v[226:227], v[228:229], s[94:95] op_sel_hi:[1,1,0]
	v_pk_fma_f32 v[222:223], v[220:221], v[222:223], s[96:97] op_sel_hi:[1,1,0]
	v_pk_fma_f32 v[228:229], v[226:227], v[228:229], s[96:97] op_sel_hi:[1,1,0]
	v_pk_fma_f32 v[222:223], v[220:221], v[222:223], s[98:99] op_sel_hi:[1,1,0]
	v_pk_fma_f32 v[228:229], v[226:227], v[228:229], s[98:99] op_sel_hi:[1,1,0]
	v_pk_mul_f32 v[222:223], v[220:221], v[222:223]
	v_pk_mul_f32 v[228:229], v[226:227], v[228:229]
	v_pk_mul_f32 v[222:223], v[224:225], v[222:223]
	v_pk_mul_f32 v[228:229], v[230:231], v[228:229]
	v_max_f32_e32 v220, 0, v158
	v_max_f32_e32 v221, 0, v159
	v_max_f32_e32 v226, 0, v140
	v_max_f32_e32 v227, 0, v141
	v_fma_f32 v158, -|v158|, v222, v220
	v_fma_f32 v159, -|v159|, v223, v221
	v_fma_f32 v140, -|v140|, v228, v226
	v_fma_f32 v141, -|v141|, v229, v227
	v_fma_f32 v220, |v138|, s88, 1.0
	v_fma_f32 v221, |v139|, s88, 1.0
	v_fma_f32 v226, |v162|, s88, 1.0
	v_fma_f32 v227, |v163|, s88, 1.0
; __device__ __forceinline__ unsigned pk_bf16(float lo, float hi) { f32x2 v = {lo, hi}; bf16x2_t b = __builtin_convertvector(v, bf16x2_t); return __builtin_bit_cast(unsigned, b); }
; __device__ __forceinline__ f32x4 gelu4(f32x4 v) { f32x2 a = gelu_pk((f32x2){v[0], v[1]}), b = gelu_pk((f32x2){v[2], v[3]}); return (f32x4){a.x, a.y, b.x, b.y}; }
; __device__ __forceinline__ f32x2 gelu_pk(f32x2 v) {
;     const f32x2 av = __builtin_elementwise_abs(v), d = av * 0.2316418882f + 1.0f;
;     f32x2 t; t.x = __builtin_amdgcn_rcpf(d.x); t.y = __builtin_amdgcn_rcpf(d.y);
;     f32x2 q = t * 0.5307027145f + (-0.7265760135f); q = q * t + 0.7107068705f; q = q * t + (-0.142248368f); q = q * t + 0.127414796f; q = q * t;
;     const f32x2 s = (v * v) * (-0.72134752044f);
;     f32x2 e; e.x = __builtin_amdgcn_exp2f(s.x); e.y = __builtin_amdgcn_exp2f(s.y);
;     const f32x2 m = v * (q * e), r = v - m;
;     f32x2 o; o.x = v.x < 0.f ? m.x : r.x; o.y = v.y < 0.f ? m.y : r.y; return o;
; }
;     __device__ __forceinline__ void operator()(const f32x4 (&acc)[2][2][4][2], const Unit& u, int wr, int wc, int fr, int fq, float rp0, float rp1, const f32x4& raw0, const f32x4& raw1, float& rn0, float& rn1) const {
;     ...
;                 for (int k = 0; k < 4; ++k) rs[k] = __shfl(ai ? rp1 : rp0, fr + 16 * k);
; #pragma unroll
;                 for (int m = 0; m < 4; ++m) {
;                     const int roff = ai * HALF + m * 16; const float r = rs[m];
; #pragma unroll
;                     for (int bj = 0; bj < 2; ++bj) {
;                         f32x4 v0 = acc[ai][bj][m][0] * r, v1 = acc[ai][bj][m][1] * r;
;                         if (gel) { v0 = gelu4(v0); v1 = gelu4(v1); }
;                         u32x4 w; w.x = pk_bf16(v0[0], v0[1]); w.y = pk_bf16(v0[2], v0[3]); w.z = pk_bf16(v1[0], v1[1]); w.w = pk_bf16(v1[2], v1[3]);
;                         *(u32x4*)(base + (size_t)roff * ld + bj * 32) = w;
;                     }
	v_pk_mul_f32 v[224:225], v[138:139], v[138:139]
	v_pk_mul_f32 v[230:231], v[162:163], v[162:163]
	v_rcp_f32_e32 v220, v220
	v_rcp_f32_e32 v221, v221
	v_rcp_f32_e32 v226, v226
	v_rcp_f32_e32 v227, v227
	v_pk_mul_f32 v[224:225], v[224:225], s[72:73] op_sel_hi:[1,0]
	v_pk_mul_f32 v[230:231], v[230:231], s[72:73] op_sel_hi:[1,0]
	v_pk_fma_f32 v[222:223], v[220:221], s[90:91], v[232:233] op_sel_hi:[1,0,0]
	v_pk_fma_f32 v[228:229], v[226:227], s[90:91], v[232:233] op_sel_hi:[1,0,0]
	v_exp_f32_e32 v224, v224
	v_exp_f32_e32 v225, v225
	v_exp_f32_e32 v230, v230
	v_exp_f32_e32 v231, v231
	v_pk_fma_f32 v[222:223], v[220:221], v[222:223], s[94:95] op_sel_hi:[1,1,0]
	v_pk_fma_f32 v[228:229], v[226:227], v[228:229], s[94:95] op_sel_hi:[1,1,0]
	v_pk_fma_f32 v[222:223], v[220:221], v[222:223], s[96:97] op_sel_hi:[1,1,0]
	v_pk_fma_f32 v[228:229], v[226:227], v[228:229], s[96:97] op_sel_hi:[1,1,0]
	v_pk_fma_f32 v[222:223], v[220:221], v[222:223], s[98:99] op_sel_hi:[1,1,0]
	v_pk_fma_f32 v[228:229], v[226:227], v[228:229], s[98:99] op_sel_hi:[1,1,0]
	v_pk_mul_f32 v[222:223], v[220:221], v[222:223]
	v_pk_mul_f32 v[228:229], v[226:227], v[228:229]
	v_pk_mul_f32 v[222:223], v[224:225], v[222:223]
	v_pk_mul_f32 v[228:229], v[230:231], v[228:229]
	v_max_f32_e32 v220, 0, v138
	v_max_f32_e32 v221, 0, v139
	v_max_f32_e32 v226, 0, v162
	v_max_f32_e32 v227, 0, v163
	v_fma_f32 v138, -|v138|, v222, v220
	v_fma_f32 v139, -|v139|, v223, v221
	v_fma_f32 v162, -|v162|, v228, v226
	v_fma_f32 v163, -|v163|, v229, v227
.LBB0_148:
	v_or_b32_e32 v168, 64, v170
	v_or_b32_e32 v169, 0x80, v170
	v_or_b32_e32 v171, 0xc0, v170
	v_cvt_pk_bf16_f32 v167, v162, v163
	ds_bpermute_b32 v162, v170, v154
	v_cvt_pk_bf16_f32 v164, v158, v159
	v_cvt_pk_bf16_f32 v165, v140, v141
	v_cvt_pk_bf16_f32 v166, v138, v139
	ds_bpermute_b32 v158, v168, v154
	ds_bpermute_b32 v140, v169, v154
	ds_bpermute_b32 v138, v171, v154
	global_store_dwordx4 v[160:161], v[164:167], off offset:64
	s_waitcnt lgkmcnt(0)
	v_pk_mul_f32 v[168:169], v[48:49], v[162:163] op_sel_hi:[1,0]
	s_and_b64 vcc, exec, s[6:7]
	v_pk_mul_f32 v[164:165], v[44:45], v[162:163] op_sel_hi:[1,0]
	v_pk_mul_f32 v[166:167], v[42:43], v[162:163] op_sel_hi:[1,0]
	v_pk_mul_f32 v[170:171], v[46:47], v[162:163] op_sel_hi:[1,0]
	s_cbranch_vccnz .LBB0_150
	v_fma_f32 v220, |v166|, s88, 1.0
	v_fma_f32 v221, |v167|, s88, 1.0
	v_fma_f32 v226, |v164|, s88, 1.0
	v_fma_f32 v227, |v165|, s88, 1.0
	v_pk_mul_f32 v[224:225], v[166:167], v[166:167]
	v_pk_mul_f32 v[230:231], v[164:165], v[164:165]
	v_rcp_f32_e32 v220, v220
	v_rcp_f32_e32 v221, v221
	v_rcp_f32_e32 v226, v226
	v_rcp_f32_e32 v227, v227
	v_pk_mul_f32 v[224:225], v[224:225], s[72:73] op_sel_hi:[1,0]
	v_pk_mul_f32 v[230:231], v[230:231], s[72:73] op_sel_hi:[1,0]
	v_pk_fma_f32 v[222:223], v[220:221], s[90:91], v[232:233] op_sel_hi:[1,0,0]
	v_pk_fma_f32 v[228:229], v[226:227], s[90:91], v[232:233] op_sel_hi:[1,0,0]
	v_exp_f32_e32 v224, v224
	v_exp_f32_e32 v225, v225
	v_exp_f32_e32 v230, v230
	v_exp_f32_e32 v231, v231
	v_pk_fma_f32 v[222:223], v[220:221], v[222:223], s[94:95] op_sel_hi:[1,1,0]
	v_pk_fma_f32 v[228:229], v[226:227], v[228:229], s[94:95] op_sel_hi:[1,1,0]
	v_pk_fma_f32 v[222:223], v[220:221], v[222:223], s[96:97] op_sel_hi:[1,1,0]
	v_pk_fma_f32 v[228:229], v[226:227], v[228:229], s[96:97] op_sel_hi:[1,1,0]
	v_pk_fma_f32 v[222:223], v[220:221], v[222:223], s[98:99] op_sel_hi:[1,1,0]
	v_pk_fma_f32 v[228:229], v[226:227], v[228:229], s[98:99] op_sel_hi:[1,1,0]
	v_pk_mul_f32 v[222:223], v[220:221], v[222:223]
	v_pk_mul_f32 v[228:229], v[226:227], v[228:229]
	v_pk_mul_f32 v[222:223], v[224:225], v[222:223]
	v_pk_mul_f32 v[228:229], v[230:231], v[228:229]
	v_max_f32_e32 v220, 0, v166
	v_max_f32_e32 v221, 0, v167
	v_max_f32_e32 v226, 0, v164
	v_max_f32_e32 v227, 0, v165
	v_fma_f32 v166, -|v166|, v222, v220
	v_fma_f32 v167, -|v167|, v223, v221
	v_fma_f32 v164, -|v164|, v228, v226
	v_fma_f32 v165, -|v165|, v229, v227
	v_fma_f32 v220, |v170|, s88, 1.0
	v_fma_f32 v221, |v171|, s88, 1.0
	v_fma_f32 v226, |v168|, s88, 1.0
	v_fma_f32 v227, |v169|, s88, 1.0
	v_pk_mul_f32 v[224:225], v[170:171], v[170:171]
	v_pk_mul_f32 v[230:231], v[168:169], v[168:169]
	v_rcp_f32_e32 v220, v220
	v_rcp_f32_e32 v221, v221
	v_rcp_f32_e32 v226, v226
	v_rcp_f32_e32 v227, v227
	v_pk_mul_f32 v[224:225], v[224:225], s[72:73] op_sel_hi:[1,0]
	v_pk_mul_f32 v[230:231], v[230:231], s[72:73] op_sel_hi:[1,0]
	v_pk_fma_f32 v[222:223], v[220:221], s[90:91], v[232:233] op_sel_hi:[1,0,0]
	v_pk_fma_f32 v[228:229], v[226:227], s[90:91], v[232:233] op_sel_hi:[1,0,0]
	v_exp_f32_e32 v224, v224
	v_exp_f32_e32 v225, v225
	v_exp_f32_e32 v230, v230
	v_exp_f32_e32 v231, v231
	v_pk_fma_f32 v[222:223], v[220:221], v[222:223], s[94:95] op_sel_hi:[1,1,0]
	v_pk_fma_f32 v[228:229], v[226:227], v[228:229], s[94:95] op_sel_hi:[1,1,0]
	v_pk_fma_f32 v[222:223], v[220:221], v[222:223], s[96:97] op_sel_hi:[1,1,0]
	v_pk_fma_f32 v[228:229], v[226:227], v[228:229], s[96:97] op_sel_hi:[1,1,0]
	v_pk_fma_f32 v[222:223], v[220:221], v[222:223], s[98:99] op_sel_hi:[1,1,0]
	v_pk_fma_f32 v[228:229], v[226:227], v[228:229], s[98:99] op_sel_hi:[1,1,0]
	v_pk_mul_f32 v[222:223], v[220:221], v[222:223]
	v_pk_mul_f32 v[228:229], v[226:227], v[228:229]
	v_pk_mul_f32 v[222:223], v[224:225], v[222:223]
	v_pk_mul_f32 v[228:229], v[230:231], v[228:229]
	v_max_f32_e32 v220, 0, v170
	v_max_f32_e32 v221, 0, v171
	v_max_f32_e32 v226, 0, v168
	v_max_f32_e32 v227, 0, v169
	v_fma_f32 v170, -|v170|, v222, v220
	v_fma_f32 v171, -|v171|, v223, v221
	v_fma_f32 v168, -|v168|, v228, v226
	v_fma_f32 v169, -|v169|, v229, v227
; __device__ __forceinline__ unsigned pk_bf16(float lo, float hi) { f32x2 v = {lo, hi}; bf16x2_t b = __builtin_convertvector(v, bf16x2_t); return __builtin_bit_cast(unsigned, b); }
; __device__ __forceinline__ f32x4 gelu4(f32x4 v) { f32x2 a = gelu_pk((f32x2){v[0], v[1]}), b = gelu_pk((f32x2){v[2], v[3]}); return (f32x4){a.x, a.y, b.x, b.y}; }
; __device__ __forceinline__ f32x2 gelu_pk(f32x2 v) {
;     const f32x2 av = __builtin_elementwise_abs(v), d = av * 0.2316418882f + 1.0f;
;     f32x2 t; t.x = __builtin_amdgcn_rcpf(d.x); t.y = __builtin_amdgcn_rcpf(d.y);
;     f32x2 q = t * 0.5307027145f + (-0.7265760135f); q = q * t + 0.7107068705f; q = q * t + (-0.142248368f); q = q * t + 0.127414796f; q = q * t;
;     const f32x2 s = (v * v) * (-0.72134752044f);
;     f32x2 e; e.x = __builtin_amdgcn_exp2f(s.x); e.y = __builtin_amdgcn_exp2f(s.y);
;     const f32x2 m = v * (q * e), r = v - m;
;     f32x2 o; o.x = v.x < 0.f ? m.x : r.x; o.y = v.y < 0.f ? m.y : r.y; return o;
; }
;     __device__ __forceinline__ void operator()(const f32x4 (&acc)[2][2][4][2], const Unit& u, int wr, int wc, int fr, int fq, float rp0, float rp1, const f32x4& raw0, const f32x4& raw1, float& rn0, float& rn1) const {
;     ...
;                 for (int m = 0; m < 4; ++m) {
;                     const int roff = ai * HALF + m * 16; const float r = rs[m];
; #pragma unroll
;                     for (int bj = 0; bj < 2; ++bj) {
;                         f32x4 v0 = acc[ai][bj][m][0] * r, v1 = acc[ai][bj][m][1] * r;
;                         if (gel) { v0 = gelu4(v0); v1 = gelu4(v1); }
;                         u32x4 w; w.x = pk_bf16(v0[0], v0[1]); w.y = pk_bf16(v0[2], v0[3]); w.z = pk_bf16(v1[0], v1[1]); w.w = pk_bf16(v1[2], v1[3]);
;                         *(u32x4*)(base + (size_t)roff * ld + bj * 32) = w;
;                     }
.LBB0_150:
	v_mov_b32_e32 v163, v162
	v_cvt_pk_bf16_f32 v177, v168, v169
	v_mov_b32_e32 v168, v162
	v_mov_b32_e32 v169, v162
	v_mad_u64_u32 v[160:161], s[40:41], s10, v217, v[160:161]
	v_cvt_pk_bf16_f32 v174, v166, v167
	v_cvt_pk_bf16_f32 v175, v164, v165
	v_cvt_pk_bf16_f32 v176, v170, v171
	v_pk_mul_f32 v[164:165], v[60:61], v[168:169]
	v_pk_mul_f32 v[166:167], v[58:59], v[162:163]
	v_pk_mul_f32 v[168:169], v[64:65], v[168:169]
	s_and_b64 vcc, exec, s[6:7]
	v_pk_mul_f32 v[162:163], v[62:63], v[162:163]
	global_store_dwordx4 v[160:161], v[174:177], off
	s_cbranch_vccnz .LBB0_152
	v_fma_f32 v220, |v166|, s88, 1.0
	v_fma_f32 v221, |v167|, s88, 1.0
	v_fma_f32 v226, |v164|, s88, 1.0
	v_fma_f32 v227, |v165|, s88, 1.0
	v_pk_mul_f32 v[224:225], v[166:167], v[166:167]
	v_pk_mul_f32 v[230:231], v[164:165], v[164:165]
	v_rcp_f32_e32 v220, v220
	v_rcp_f32_e32 v221, v221
	v_rcp_f32_e32 v226, v226
	v_rcp_f32_e32 v227, v227
	v_pk_mul_f32 v[224:225], v[224:225], s[72:73] op_sel_hi:[1,0]
	v_pk_mul_f32 v[230:231], v[230:231], s[72:73] op_sel_hi:[1,0]
	v_pk_fma_f32 v[222:223], v[220:221], s[90:91], v[232:233] op_sel_hi:[1,0,0]
	v_pk_fma_f32 v[228:229], v[226:227], s[90:91], v[232:233] op_sel_hi:[1,0,0]
	v_exp_f32_e32 v224, v224
	v_exp_f32_e32 v225, v225
	v_exp_f32_e32 v230, v230
	v_exp_f32_e32 v231, v231
	v_pk_fma_f32 v[222:223], v[220:221], v[222:223], s[94:95] op_sel_hi:[1,1,0]
	v_pk_fma_f32 v[228:229], v[226:227], v[228:229], s[94:95] op_sel_hi:[1,1,0]
	v_pk_fma_f32 v[222:223], v[220:221], v[222:223], s[96:97] op_sel_hi:[1,1,0]
	v_pk_fma_f32 v[228:229], v[226:227], v[228:229], s[96:97] op_sel_hi:[1,1,0]
	v_pk_fma_f32 v[222:223], v[220:221], v[222:223], s[98:99] op_sel_hi:[1,1,0]
	v_pk_fma_f32 v[228:229], v[226:227], v[228:229], s[98:99] op_sel_hi:[1,1,0]
	v_pk_mul_f32 v[222:223], v[220:221], v[222:223]
	v_pk_mul_f32 v[228:229], v[226:227], v[228:229]
	v_pk_mul_f32 v[222:223], v[224:225], v[222:223]
	v_pk_mul_f32 v[228:229], v[230:231], v[228:229]
	v_max_f32_e32 v220, 0, v166
	v_max_f32_e32 v221, 0, v167
	v_max_f32_e32 v226, 0, v164
	v_max_f32_e32 v227, 0, v165
	v_fma_f32 v166, -|v166|, v222, v220
	v_fma_f32 v167, -|v167|, v223, v221
	v_fma_f32 v164, -|v164|, v228, v226
	v_fma_f32 v165, -|v165|, v229, v227
	v_fma_f32 v220, |v162|, s88, 1.0
	v_fma_f32 v221, |v163|, s88, 1.0
	v_fma_f32 v226, |v168|, s88, 1.0
	v_fma_f32 v227, |v169|, s88, 1.0
	v_pk_mul_f32 v[224:225], v[162:163], v[162:163]
	v_pk_mul_f32 v[230:231], v[168:169], v[168:169]
	v_rcp_f32_e32 v220, v220
	v_rcp_f32_e32 v221, v221
	v_rcp_f32_e32 v226, v226
	v_rcp_f32_e32 v227, v227
	v_pk_mul_f32 v[224:225], v[224:225], s[72:73] op_sel_hi:[1,0]
	v_pk_mul_f32 v[230:231], v[230:231], s[72:73] op_sel_hi:[1,0]
	v_pk_fma_f32 v[222:223], v[220:221], s[90:91], v[232:233] op_sel_hi:[1,0,0]
	v_pk_fma_f32 v[228:229], v[226:227], s[90:91], v[232:233] op_sel_hi:[1,0,0]
	v_exp_f32_e32 v224, v224
	v_exp_f32_e32 v225, v225
	v_exp_f32_e32 v230, v230
	v_exp_f32_e32 v231, v231
	v_pk_fma_f32 v[222:223], v[220:221], v[222:223], s[94:95] op_sel_hi:[1,1,0]
	v_pk_fma_f32 v[228:229], v[226:227], v[228:229], s[94:95] op_sel_hi:[1,1,0]
	v_pk_fma_f32 v[222:223], v[220:221], v[222:223], s[96:97] op_sel_hi:[1,1,0]
	v_pk_fma_f32 v[228:229], v[226:227], v[228:229], s[96:97] op_sel_hi:[1,1,0]
	v_pk_fma_f32 v[222:223], v[220:221], v[222:223], s[98:99] op_sel_hi:[1,1,0]
	v_pk_fma_f32 v[228:229], v[226:227], v[228:229], s[98:99] op_sel_hi:[1,1,0]
	v_pk_mul_f32 v[222:223], v[220:221], v[222:223]
	v_pk_mul_f32 v[228:229], v[226:227], v[228:229]
	v_pk_mul_f32 v[222:223], v[224:225], v[222:223]
	v_pk_mul_f32 v[228:229], v[230:231], v[228:229]
	v_max_f32_e32 v220, 0, v162
	v_max_f32_e32 v221, 0, v163
	v_max_f32_e32 v226, 0, v168
	v_max_f32_e32 v227, 0, v169
	v_fma_f32 v162, -|v162|, v222, v220
	v_fma_f32 v163, -|v163|, v223, v221
	v_fma_f32 v168, -|v168|, v228, v226
	v_fma_f32 v169, -|v169|, v229, v227
.LBB0_152:
	s_nop 0
	v_cvt_pk_bf16_f32 v174, v166, v167
	v_cvt_pk_bf16_f32 v175, v164, v165
	v_cvt_pk_bf16_f32 v176, v162, v163
	v_cvt_pk_bf16_f32 v177, v168, v169
	v_pk_mul_f32 v[162:163], v[36:37], v[158:159] op_sel_hi:[1,0]
	v_pk_mul_f32 v[164:165], v[34:35], v[158:159] op_sel_hi:[1,0]
	v_pk_mul_f32 v[166:167], v[40:41], v[158:159] op_sel_hi:[1,0]
	s_and_b64 vcc, exec, s[6:7]
	v_pk_mul_f32 v[168:169], v[38:39], v[158:159] op_sel_hi:[1,0]
	global_store_dwordx4 v[160:161], v[174:177], off offset:64
	s_cbranch_vccnz .LBB0_154
; __device__ __forceinline__ unsigned pk_bf16(float lo, float hi) { f32x2 v = {lo, hi}; bf16x2_t b = __builtin_convertvector(v, bf16x2_t); return __builtin_bit_cast(unsigned, b); }
; __device__ __forceinline__ f32x4 gelu4(f32x4 v) { f32x2 a = gelu_pk((f32x2){v[0], v[1]}), b = gelu_pk((f32x2){v[2], v[3]}); return (f32x4){a.x, a.y, b.x, b.y}; }
; __device__ __forceinline__ f32x2 gelu_pk(f32x2 v) {
;     const f32x2 av = __builtin_elementwise_abs(v), d = av * 0.2316418882f + 1.0f;
;     f32x2 t; t.x = __builtin_amdgcn_rcpf(d.x); t.y = __builtin_amdgcn_rcpf(d.y);
;     f32x2 q = t * 0.5307027145f + (-0.7265760135f); q = q * t + 0.7107068705f; q = q * t + (-0.142248368f); q = q * t + 0.127414796f; q = q * t;
;     const f32x2 s = (v * v) * (-0.72134752044f);
;     f32x2 e; e.x = __builtin_amdgcn_exp2f(s.x); e.y = __builtin_amdgcn_exp2f(s.y);
;     const f32x2 m = v * (q * e), r = v - m;
;     f32x2 o; o.x = v.x < 0.f ? m.x : r.x; o.y = v.y < 0.f ? m.y : r.y; return o;
; }
;     __device__ __forceinline__ void operator()(const f32x4 (&acc)[2][2][4][2], const Unit& u, int wr, int wc, int fr, int fq, float rp0, float rp1, const f32x4& raw0, const f32x4& raw1, float& rn0, float& rn1) const {
;     ...
;                 for (int m = 0; m < 4; ++m) {
;                     const int roff = ai * HALF + m * 16; const float r = rs[m];
; #pragma unroll
;                     for (int bj = 0; bj < 2; ++bj) {
;                         f32x4 v0 = acc[ai][bj][m][0] * r, v1 = acc[ai][bj][m][1] * r;
;                         if (gel) { v0 = gelu4(v0); v1 = gelu4(v1); }
;                         u32x4 w; w.x = pk_bf16(v0[0], v0[1]); w.y = pk_bf16(v0[2], v0[3]); w.z = pk_bf16(v1[0], v1[1]); w.w = pk_bf16(v1[2], v1[3]);
;                         *(u32x4*)(base + (size_t)roff * ld + bj * 32) = w;
;                     }
	v_fma_f32 v220, |v164|, s88, 1.0
	v_fma_f32 v221, |v165|, s88, 1.0
	v_fma_f32 v226, |v162|, s88, 1.0
	v_fma_f32 v227, |v163|, s88, 1.0
	v_pk_mul_f32 v[224:225], v[164:165], v[164:165]
	v_pk_mul_f32 v[230:231], v[162:163], v[162:163]
	v_rcp_f32_e32 v220, v220
	v_rcp_f32_e32 v221, v221
	v_rcp_f32_e32 v226, v226
	v_rcp_f32_e32 v227, v227
	v_pk_mul_f32 v[224:225], v[224:225], s[72:73] op_sel_hi:[1,0]
	v_pk_mul_f32 v[230:231], v[230:231], s[72:73] op_sel_hi:[1,0]
	v_pk_fma_f32 v[222:223], v[220:221], s[90:91], v[232:233] op_sel_hi:[1,0,0]
	v_pk_fma_f32 v[228:229], v[226:227], s[90:91], v[232:233] op_sel_hi:[1,0,0]
	v_exp_f32_e32 v224, v224
	v_exp_f32_e32 v225, v225
	v_exp_f32_e32 v230, v230
	v_exp_f32_e32 v231, v231
	v_pk_fma_f32 v[222:223], v[220:221], v[222:223], s[94:95] op_sel_hi:[1,1,0]
	v_pk_fma_f32 v[228:229], v[226:227], v[228:229], s[94:95] op_sel_hi:[1,1,0]
	v_pk_fma_f32 v[222:223], v[220:221], v[222:223], s[96:97] op_sel_hi:[1,1,0]
	v_pk_fma_f32 v[228:229], v[226:227], v[228:229], s[96:97] op_sel_hi:[1,1,0]
	v_pk_fma_f32 v[222:223], v[220:221], v[222:223], s[98:99] op_sel_hi:[1,1,0]
	v_pk_fma_f32 v[228:229], v[226:227], v[228:229], s[98:99] op_sel_hi:[1,1,0]
	v_pk_mul_f32 v[222:223], v[220:221], v[222:223]
	v_pk_mul_f32 v[228:229], v[226:227], v[228:229]
	v_pk_mul_f32 v[222:223], v[224:225], v[222:223]
	v_pk_mul_f32 v[228:229], v[230:231], v[228:229]
	v_max_f32_e32 v220, 0, v164
	v_max_f32_e32 v221, 0, v165
	v_max_f32_e32 v226, 0, v162
	v_max_f32_e32 v227, 0, v163
	v_fma_f32 v164, -|v164|, v222, v220
	v_fma_f32 v165, -|v165|, v223, v221
	v_fma_f32 v162, -|v162|, v228, v226
	v_fma_f32 v163, -|v163|, v229, v227
	v_fma_f32 v220, |v168|, s88, 1.0
	v_fma_f32 v221, |v169|, s88, 1.0
	v_fma_f32 v226, |v166|, s88, 1.0
	v_fma_f32 v227, |v167|, s88, 1.0
	v_pk_mul_f32 v[224:225], v[168:169], v[168:169]
	v_pk_mul_f32 v[230:231], v[166:167], v[166:167]
	v_rcp_f32_e32 v220, v220
	v_rcp_f32_e32 v221, v221
	v_rcp_f32_e32 v226, v226
	v_rcp_f32_e32 v227, v227
	v_pk_mul_f32 v[224:225], v[224:225], s[72:73] op_sel_hi:[1,0]
	v_pk_mul_f32 v[230:231], v[230:231], s[72:73] op_sel_hi:[1,0]
	v_pk_fma_f32 v[222:223], v[220:221], s[90:91], v[232:233] op_sel_hi:[1,0,0]
	v_pk_fma_f32 v[228:229], v[226:227], s[90:91], v[232:233] op_sel_hi:[1,0,0]
	v_exp_f32_e32 v224, v224
	v_exp_f32_e32 v225, v225
	v_exp_f32_e32 v230, v230
	v_exp_f32_e32 v231, v231
	v_pk_fma_f32 v[222:223], v[220:221], v[222:223], s[94:95] op_sel_hi:[1,1,0]
	v_pk_fma_f32 v[228:229], v[226:227], v[228:229], s[94:95] op_sel_hi:[1,1,0]
	v_pk_fma_f32 v[222:223], v[220:221], v[222:223], s[96:97] op_sel_hi:[1,1,0]
	v_pk_fma_f32 v[228:229], v[226:227], v[228:229], s[96:97] op_sel_hi:[1,1,0]
	v_pk_fma_f32 v[222:223], v[220:221], v[222:223], s[98:99] op_sel_hi:[1,1,0]
	v_pk_fma_f32 v[228:229], v[226:227], v[228:229], s[98:99] op_sel_hi:[1,1,0]
	v_pk_mul_f32 v[222:223], v[220:221], v[222:223]
	v_pk_mul_f32 v[228:229], v[226:227], v[228:229]
	v_pk_mul_f32 v[222:223], v[224:225], v[222:223]
	v_pk_mul_f32 v[228:229], v[230:231], v[228:229]
	v_max_f32_e32 v220, 0, v168
	v_max_f32_e32 v221, 0, v169
	v_max_f32_e32 v226, 0, v166
	v_max_f32_e32 v227, 0, v167
	v_fma_f32 v168, -|v168|, v222, v220
	v_fma_f32 v169, -|v169|, v223, v221
	v_fma_f32 v166, -|v166|, v228, v226
	v_fma_f32 v167, -|v167|, v229, v227
.LBB0_154:
	v_mov_b32_e32 v159, v158
	v_cvt_pk_bf16_f32 v177, v166, v167
	v_mov_b32_e32 v166, v158
	v_mov_b32_e32 v167, v158
	v_lshl_add_u64 v[160:161], v[160:161], 0, s[76:77]
	v_cvt_pk_bf16_f32 v174, v164, v165
	v_cvt_pk_bf16_f32 v175, v162, v163
	v_cvt_pk_bf16_f32 v176, v168, v169
	v_pk_mul_f32 v[162:163], v[52:53], v[166:167]
	v_pk_mul_f32 v[164:165], v[50:51], v[158:159]
	v_pk_mul_f32 v[166:167], v[56:57], v[166:167]
	s_and_b64 vcc, exec, s[6:7]
	v_pk_mul_f32 v[158:159], v[54:55], v[158:159]
	global_store_dwordx4 v[160:161], v[174:177], off
	s_cbranch_vccnz .LBB0_156
	v_fma_f32 v220, |v164|, s88, 1.0
	v_fma_f32 v221, |v165|, s88, 1.0
	v_fma_f32 v226, |v162|, s88, 1.0
	v_fma_f32 v227, |v163|, s88, 1.0
	v_pk_mul_f32 v[224:225], v[164:165], v[164:165]
	v_pk_mul_f32 v[230:231], v[162:163], v[162:163]
	v_rcp_f32_e32 v220, v220
	v_rcp_f32_e32 v221, v221
	v_rcp_f32_e32 v226, v226
	v_rcp_f32_e32 v227, v227
	v_pk_mul_f32 v[224:225], v[224:225], s[72:73] op_sel_hi:[1,0]
	v_pk_mul_f32 v[230:231], v[230:231], s[72:73] op_sel_hi:[1,0]
	v_pk_fma_f32 v[222:223], v[220:221], s[90:91], v[232:233] op_sel_hi:[1,0,0]
	v_pk_fma_f32 v[228:229], v[226:227], s[90:91], v[232:233] op_sel_hi:[1,0,0]
	v_exp_f32_e32 v224, v224
	v_exp_f32_e32 v225, v225
	v_exp_f32_e32 v230, v230
	v_exp_f32_e32 v231, v231
	v_pk_fma_f32 v[222:223], v[220:221], v[222:223], s[94:95] op_sel_hi:[1,1,0]
	v_pk_fma_f32 v[228:229], v[226:227], v[228:229], s[94:95] op_sel_hi:[1,1,0]
	v_pk_fma_f32 v[222:223], v[220:221], v[222:223], s[96:97] op_sel_hi:[1,1,0]
	v_pk_fma_f32 v[228:229], v[226:227], v[228:229], s[96:97] op_sel_hi:[1,1,0]
	v_pk_fma_f32 v[222:223], v[220:221], v[222:223], s[98:99] op_sel_hi:[1,1,0]
	v_pk_fma_f32 v[228:229], v[226:227], v[228:229], s[98:99] op_sel_hi:[1,1,0]
	v_pk_mul_f32 v[222:223], v[220:221], v[222:223]
	v_pk_mul_f32 v[228:229], v[226:227], v[228:229]
	v_pk_mul_f32 v[222:223], v[224:225], v[222:223]
	v_pk_mul_f32 v[228:229], v[230:231], v[228:229]
	v_max_f32_e32 v220, 0, v164
	v_max_f32_e32 v221, 0, v165
	v_max_f32_e32 v226, 0, v162
	v_max_f32_e32 v227, 0, v163
	v_fma_f32 v164, -|v164|, v222, v220
	v_fma_f32 v165, -|v165|, v223, v221
	v_fma_f32 v162, -|v162|, v228, v226
	v_fma_f32 v163, -|v163|, v229, v227
	v_fma_f32 v220, |v158|, s88, 1.0
	v_fma_f32 v221, |v159|, s88, 1.0
	v_fma_f32 v226, |v166|, s88, 1.0
	v_fma_f32 v227, |v167|, s88, 1.0
; __device__ __forceinline__ unsigned pk_bf16(float lo, float hi) { f32x2 v = {lo, hi}; bf16x2_t b = __builtin_convertvector(v, bf16x2_t); return __builtin_bit_cast(unsigned, b); }
; __device__ __forceinline__ f32x4 gelu4(f32x4 v) { f32x2 a = gelu_pk((f32x2){v[0], v[1]}), b = gelu_pk((f32x2){v[2], v[3]}); return (f32x4){a.x, a.y, b.x, b.y}; }
; __device__ __forceinline__ f32x2 gelu_pk(f32x2 v) {
;     const f32x2 av = __builtin_elementwise_abs(v), d = av * 0.2316418882f + 1.0f;
;     f32x2 t; t.x = __builtin_amdgcn_rcpf(d.x); t.y = __builtin_amdgcn_rcpf(d.y);
;     f32x2 q = t * 0.5307027145f + (-0.7265760135f); q = q * t + 0.7107068705f; q = q * t + (-0.142248368f); q = q * t + 0.127414796f; q = q * t;
;     const f32x2 s = (v * v) * (-0.72134752044f);
;     f32x2 e; e.x = __builtin_amdgcn_exp2f(s.x); e.y = __builtin_amdgcn_exp2f(s.y);
;     const f32x2 m = v * (q * e), r = v - m;
;     f32x2 o; o.x = v.x < 0.f ? m.x : r.x; o.y = v.y < 0.f ? m.y : r.y; return o;
; }
;     __device__ __forceinline__ void operator()(const f32x4 (&acc)[2][2][4][2], const Unit& u, int wr, int wc, int fr, int fq, float rp0, float rp1, const f32x4& raw0, const f32x4& raw1, float& rn0, float& rn1) const {
;     ...
;                 for (int m = 0; m < 4; ++m) {
;                     const int roff = ai * HALF + m * 16; const float r = rs[m];
; #pragma unroll
;                     for (int bj = 0; bj < 2; ++bj) {
;                         f32x4 v0 = acc[ai][bj][m][0] * r, v1 = acc[ai][bj][m][1] * r;
;                         if (gel) { v0 = gelu4(v0); v1 = gelu4(v1); }
;                         u32x4 w; w.x = pk_bf16(v0[0], v0[1]); w.y = pk_bf16(v0[2], v0[3]); w.z = pk_bf16(v1[0], v1[1]); w.w = pk_bf16(v1[2], v1[3]);
;                         *(u32x4*)(base + (size_t)roff * ld + bj * 32) = w;
;                     }
	v_pk_mul_f32 v[224:225], v[158:159], v[158:159]
	v_pk_mul_f32 v[230:231], v[166:167], v[166:167]
	v_rcp_f32_e32 v220, v220
	v_rcp_f32_e32 v221, v221
	v_rcp_f32_e32 v226, v226
	v_rcp_f32_e32 v227, v227
	v_pk_mul_f32 v[224:225], v[224:225], s[72:73] op_sel_hi:[1,0]
	v_pk_mul_f32 v[230:231], v[230:231], s[72:73] op_sel_hi:[1,0]
	v_pk_fma_f32 v[222:223], v[220:221], s[90:91], v[232:233] op_sel_hi:[1,0,0]
	v_pk_fma_f32 v[228:229], v[226:227], s[90:91], v[232:233] op_sel_hi:[1,0,0]
	v_exp_f32_e32 v224, v224
	v_exp_f32_e32 v225, v225
	v_exp_f32_e32 v230, v230
	v_exp_f32_e32 v231, v231
	v_pk_fma_f32 v[222:223], v[220:221], v[222:223], s[94:95] op_sel_hi:[1,1,0]
	v_pk_fma_f32 v[228:229], v[226:227], v[228:229], s[94:95] op_sel_hi:[1,1,0]
	v_pk_fma_f32 v[222:223], v[220:221], v[222:223], s[96:97] op_sel_hi:[1,1,0]
	v_pk_fma_f32 v[228:229], v[226:227], v[228:229], s[96:97] op_sel_hi:[1,1,0]
	v_pk_fma_f32 v[222:223], v[220:221], v[222:223], s[98:99] op_sel_hi:[1,1,0]
	v_pk_fma_f32 v[228:229], v[226:227], v[228:229], s[98:99] op_sel_hi:[1,1,0]
	v_pk_mul_f32 v[222:223], v[220:221], v[222:223]
	v_pk_mul_f32 v[228:229], v[226:227], v[228:229]
	v_pk_mul_f32 v[222:223], v[224:225], v[222:223]
	v_pk_mul_f32 v[228:229], v[230:231], v[228:229]
	v_max_f32_e32 v220, 0, v158
	v_max_f32_e32 v221, 0, v159
	v_max_f32_e32 v226, 0, v166
	v_max_f32_e32 v227, 0, v167
	v_fma_f32 v158, -|v158|, v222, v220
	v_fma_f32 v159, -|v159|, v223, v221
	v_fma_f32 v166, -|v166|, v228, v226
	v_fma_f32 v167, -|v167|, v229, v227
.LBB0_156:
	v_cvt_pk_bf16_f32 v168, v164, v165
	v_cvt_pk_bf16_f32 v169, v162, v163
	v_cvt_pk_bf16_f32 v170, v158, v159
	v_cvt_pk_bf16_f32 v171, v166, v167
	global_store_dwordx4 v[160:161], v[168:171], off offset:64
	v_pk_mul_f32 v[162:163], v[12:13], v[140:141] op_sel_hi:[1,0]
	v_pk_mul_f32 v[164:165], v[10:11], v[140:141] op_sel_hi:[1,0]
	v_pk_mul_f32 v[166:167], v[16:17], v[140:141] op_sel_hi:[1,0]
	s_and_b64 vcc, exec, s[6:7]
	v_pk_mul_f32 v[168:169], v[14:15], v[140:141] op_sel_hi:[1,0]
	s_cbranch_vccnz .LBB0_158
	v_fma_f32 v220, |v164|, s88, 1.0
	v_fma_f32 v221, |v165|, s88, 1.0
	v_fma_f32 v226, |v162|, s88, 1.0
	v_fma_f32 v227, |v163|, s88, 1.0
	v_pk_mul_f32 v[224:225], v[164:165], v[164:165]
	v_pk_mul_f32 v[230:231], v[162:163], v[162:163]
	v_rcp_f32_e32 v220, v220
	v_rcp_f32_e32 v221, v221
	v_rcp_f32_e32 v226, v226
	v_rcp_f32_e32 v227, v227
	v_pk_mul_f32 v[224:225], v[224:225], s[72:73] op_sel_hi:[1,0]
	v_pk_mul_f32 v[230:231], v[230:231], s[72:73] op_sel_hi:[1,0]
	v_pk_fma_f32 v[222:223], v[220:221], s[90:91], v[232:233] op_sel_hi:[1,0,0]
	v_pk_fma_f32 v[228:229], v[226:227], s[90:91], v[232:233] op_sel_hi:[1,0,0]
	v_exp_f32_e32 v224, v224
	v_exp_f32_e32 v225, v225
	v_exp_f32_e32 v230, v230
	v_exp_f32_e32 v231, v231
	v_pk_fma_f32 v[222:223], v[220:221], v[222:223], s[94:95] op_sel_hi:[1,1,0]
	v_pk_fma_f32 v[228:229], v[226:227], v[228:229], s[94:95] op_sel_hi:[1,1,0]
	v_pk_fma_f32 v[222:223], v[220:221], v[222:223], s[96:97] op_sel_hi:[1,1,0]
	v_pk_fma_f32 v[228:229], v[226:227], v[228:229], s[96:97] op_sel_hi:[1,1,0]
	v_pk_fma_f32 v[222:223], v[220:221], v[222:223], s[98:99] op_sel_hi:[1,1,0]
	v_pk_fma_f32 v[228:229], v[226:227], v[228:229], s[98:99] op_sel_hi:[1,1,0]
	v_pk_mul_f32 v[222:223], v[220:221], v[222:223]
	v_pk_mul_f32 v[228:229], v[226:227], v[228:229]
	v_pk_mul_f32 v[222:223], v[224:225], v[222:223]
	v_pk_mul_f32 v[228:229], v[230:231], v[228:229]
	v_max_f32_e32 v220, 0, v164
	v_max_f32_e32 v221, 0, v165
	v_max_f32_e32 v226, 0, v162
	v_max_f32_e32 v227, 0, v163
	v_fma_f32 v164, -|v164|, v222, v220
	v_fma_f32 v165, -|v165|, v223, v221
	v_fma_f32 v162, -|v162|, v228, v226
	v_fma_f32 v163, -|v163|, v229, v227
	v_fma_f32 v220, |v168|, s88, 1.0
	v_fma_f32 v221, |v169|, s88, 1.0
	v_fma_f32 v226, |v166|, s88, 1.0
	v_fma_f32 v227, |v167|, s88, 1.0
	v_pk_mul_f32 v[224:225], v[168:169], v[168:169]
	v_pk_mul_f32 v[230:231], v[166:167], v[166:167]
	v_rcp_f32_e32 v220, v220
	v_rcp_f32_e32 v221, v221
	v_rcp_f32_e32 v226, v226
	v_rcp_f32_e32 v227, v227
	v_pk_mul_f32 v[224:225], v[224:225], s[72:73] op_sel_hi:[1,0]
	v_pk_mul_f32 v[230:231], v[230:231], s[72:73] op_sel_hi:[1,0]
	v_pk_fma_f32 v[222:223], v[220:221], s[90:91], v[232:233] op_sel_hi:[1,0,0]
	v_pk_fma_f32 v[228:229], v[226:227], s[90:91], v[232:233] op_sel_hi:[1,0,0]
	v_exp_f32_e32 v224, v224
	v_exp_f32_e32 v225, v225
	v_exp_f32_e32 v230, v230
	v_exp_f32_e32 v231, v231
	v_pk_fma_f32 v[222:223], v[220:221], v[222:223], s[94:95] op_sel_hi:[1,1,0]
	v_pk_fma_f32 v[228:229], v[226:227], v[228:229], s[94:95] op_sel_hi:[1,1,0]
	v_pk_fma_f32 v[222:223], v[220:221], v[222:223], s[96:97] op_sel_hi:[1,1,0]
	v_pk_fma_f32 v[228:229], v[226:227], v[228:229], s[96:97] op_sel_hi:[1,1,0]
	v_pk_fma_f32 v[222:223], v[220:221], v[222:223], s[98:99] op_sel_hi:[1,1,0]
	v_pk_fma_f32 v[228:229], v[226:227], v[228:229], s[98:99] op_sel_hi:[1,1,0]
	v_pk_mul_f32 v[222:223], v[220:221], v[222:223]
	v_pk_mul_f32 v[228:229], v[226:227], v[228:229]
	v_pk_mul_f32 v[222:223], v[224:225], v[222:223]
	v_pk_mul_f32 v[228:229], v[230:231], v[228:229]
	v_max_f32_e32 v220, 0, v168
	v_max_f32_e32 v221, 0, v169
	v_max_f32_e32 v226, 0, v166
	v_max_f32_e32 v227, 0, v167
	v_fma_f32 v168, -|v168|, v222, v220
	v_fma_f32 v169, -|v169|, v223, v221
	v_fma_f32 v166, -|v166|, v228, v226
	v_fma_f32 v167, -|v167|, v229, v227
; __device__ __forceinline__ unsigned pk_bf16(float lo, float hi) { f32x2 v = {lo, hi}; bf16x2_t b = __builtin_convertvector(v, bf16x2_t); return __builtin_bit_cast(unsigned, b); }
; __device__ __forceinline__ f32x4 gelu4(f32x4 v) { f32x2 a = gelu_pk((f32x2){v[0], v[1]}), b = gelu_pk((f32x2){v[2], v[3]}); return (f32x4){a.x, a.y, b.x, b.y}; }
; __device__ __forceinline__ f32x2 gelu_pk(f32x2 v) {
;     const f32x2 av = __builtin_elementwise_abs(v), d = av * 0.2316418882f + 1.0f;
;     f32x2 t; t.x = __builtin_amdgcn_rcpf(d.x); t.y = __builtin_amdgcn_rcpf(d.y);
;     f32x2 q = t * 0.5307027145f + (-0.7265760135f); q = q * t + 0.7107068705f; q = q * t + (-0.142248368f); q = q * t + 0.127414796f; q = q * t;
;     const f32x2 s = (v * v) * (-0.72134752044f);
;     f32x2 e; e.x = __builtin_amdgcn_exp2f(s.x); e.y = __builtin_amdgcn_exp2f(s.y);
;     const f32x2 m = v * (q * e), r = v - m;
;     f32x2 o; o.x = v.x < 0.f ? m.x : r.x; o.y = v.y < 0.f ? m.y : r.y; return o;
; }
;     __device__ __forceinline__ void operator()(const f32x4 (&acc)[2][2][4][2], const Unit& u, int wr, int wc, int fr, int fq, float rp0, float rp1, const f32x4& raw0, const f32x4& raw1, float& rn0, float& rn1) const {
;     ...
;                 for (int m = 0; m < 4; ++m) {
;                     const int roff = ai * HALF + m * 16; const float r = rs[m];
; #pragma unroll
;                     for (int bj = 0; bj < 2; ++bj) {
;                         f32x4 v0 = acc[ai][bj][m][0] * r, v1 = acc[ai][bj][m][1] * r;
;                         if (gel) { v0 = gelu4(v0); v1 = gelu4(v1); }
;                         u32x4 w; w.x = pk_bf16(v0[0], v0[1]); w.y = pk_bf16(v0[2], v0[3]); w.z = pk_bf16(v1[0], v1[1]); w.w = pk_bf16(v1[2], v1[3]);
;                         *(u32x4*)(base + (size_t)roff * ld + bj * 32) = w;
;                     }
.LBB0_158:
	v_mov_b32_e32 v141, v140
	v_lshl_add_u64 v[158:159], v[160:161], 0, s[76:77]
	v_cvt_pk_bf16_f32 v160, v164, v165
	v_cvt_pk_bf16_f32 v161, v162, v163
	v_cvt_pk_bf16_f32 v162, v168, v169
	v_cvt_pk_bf16_f32 v163, v166, v167
	v_mov_b32_e32 v164, v140
	v_mov_b32_e32 v165, v140
	global_store_dwordx4 v[158:159], v[160:163], off
	s_and_b64 vcc, exec, s[6:7]
	s_nop 0
	v_pk_mul_f32 v[160:161], v[28:29], v[164:165]
	v_pk_mul_f32 v[162:163], v[26:27], v[140:141]
	v_pk_mul_f32 v[164:165], v[32:33], v[164:165]
	v_pk_mul_f32 v[140:141], v[30:31], v[140:141]
	s_cbranch_vccnz .LBB0_160
	v_fma_f32 v220, |v162|, s88, 1.0
	v_fma_f32 v221, |v163|, s88, 1.0
	v_fma_f32 v226, |v160|, s88, 1.0
	v_fma_f32 v227, |v161|, s88, 1.0
	v_pk_mul_f32 v[224:225], v[162:163], v[162:163]
	v_pk_mul_f32 v[230:231], v[160:161], v[160:161]
	v_rcp_f32_e32 v220, v220
	v_rcp_f32_e32 v221, v221
	v_rcp_f32_e32 v226, v226
	v_rcp_f32_e32 v227, v227
	v_pk_mul_f32 v[224:225], v[224:225], s[72:73] op_sel_hi:[1,0]
	v_pk_mul_f32 v[230:231], v[230:231], s[72:73] op_sel_hi:[1,0]
	v_pk_fma_f32 v[222:223], v[220:221], s[90:91], v[232:233] op_sel_hi:[1,0,0]
	v_pk_fma_f32 v[228:229], v[226:227], s[90:91], v[232:233] op_sel_hi:[1,0,0]
	v_exp_f32_e32 v224, v224
	v_exp_f32_e32 v225, v225
	v_exp_f32_e32 v230, v230
	v_exp_f32_e32 v231, v231
	v_pk_fma_f32 v[222:223], v[220:221], v[222:223], s[94:95] op_sel_hi:[1,1,0]
	v_pk_fma_f32 v[228:229], v[226:227], v[228:229], s[94:95] op_sel_hi:[1,1,0]
	v_pk_fma_f32 v[222:223], v[220:221], v[222:223], s[96:97] op_sel_hi:[1,1,0]
	v_pk_fma_f32 v[228:229], v[226:227], v[228:229], s[96:97] op_sel_hi:[1,1,0]
	v_pk_fma_f32 v[222:223], v[220:221], v[222:223], s[98:99] op_sel_hi:[1,1,0]
	v_pk_fma_f32 v[228:229], v[226:227], v[228:229], s[98:99] op_sel_hi:[1,1,0]
	v_pk_mul_f32 v[222:223], v[220:221], v[222:223]
	v_pk_mul_f32 v[228:229], v[226:227], v[228:229]
	v_pk_mul_f32 v[222:223], v[224:225], v[222:223]
	v_pk_mul_f32 v[228:229], v[230:231], v[228:229]
	v_max_f32_e32 v220, 0, v162
	v_max_f32_e32 v221, 0, v163
	v_max_f32_e32 v226, 0, v160
	v_max_f32_e32 v227, 0, v161
	v_fma_f32 v162, -|v162|, v222, v220
	v_fma_f32 v163, -|v163|, v223, v221
	v_fma_f32 v160, -|v160|, v228, v226
	v_fma_f32 v161, -|v161|, v229, v227
	v_fma_f32 v220, |v140|, s88, 1.0
	v_fma_f32 v221, |v141|, s88, 1.0
	v_fma_f32 v226, |v164|, s88, 1.0
	v_fma_f32 v227, |v165|, s88, 1.0
	v_pk_mul_f32 v[224:225], v[140:141], v[140:141]
	v_pk_mul_f32 v[230:231], v[164:165], v[164:165]
	v_rcp_f32_e32 v220, v220
	v_rcp_f32_e32 v221, v221
	v_rcp_f32_e32 v226, v226
	v_rcp_f32_e32 v227, v227
	v_pk_mul_f32 v[224:225], v[224:225], s[72:73] op_sel_hi:[1,0]
	v_pk_mul_f32 v[230:231], v[230:231], s[72:73] op_sel_hi:[1,0]
	v_pk_fma_f32 v[222:223], v[220:221], s[90:91], v[232:233] op_sel_hi:[1,0,0]
	v_pk_fma_f32 v[228:229], v[226:227], s[90:91], v[232:233] op_sel_hi:[1,0,0]
	v_exp_f32_e32 v224, v224
	v_exp_f32_e32 v225, v225
	v_exp_f32_e32 v230, v230
	v_exp_f32_e32 v231, v231
	v_pk_fma_f32 v[222:223], v[220:221], v[222:223], s[94:95] op_sel_hi:[1,1,0]
	v_pk_fma_f32 v[228:229], v[226:227], v[228:229], s[94:95] op_sel_hi:[1,1,0]
	v_pk_fma_f32 v[222:223], v[220:221], v[222:223], s[96:97] op_sel_hi:[1,1,0]
	v_pk_fma_f32 v[228:229], v[226:227], v[228:229], s[96:97] op_sel_hi:[1,1,0]
	v_pk_fma_f32 v[222:223], v[220:221], v[222:223], s[98:99] op_sel_hi:[1,1,0]
	v_pk_fma_f32 v[228:229], v[226:227], v[228:229], s[98:99] op_sel_hi:[1,1,0]
	v_pk_mul_f32 v[222:223], v[220:221], v[222:223]
	v_pk_mul_f32 v[228:229], v[226:227], v[228:229]
	v_pk_mul_f32 v[222:223], v[224:225], v[222:223]
	v_pk_mul_f32 v[228:229], v[230:231], v[228:229]
	v_max_f32_e32 v220, 0, v140
	v_max_f32_e32 v221, 0, v141
	v_max_f32_e32 v226, 0, v164
	v_max_f32_e32 v227, 0, v165
	v_fma_f32 v140, -|v140|, v222, v220
	v_fma_f32 v141, -|v141|, v223, v221
	v_fma_f32 v164, -|v164|, v228, v226
	v_fma_f32 v165, -|v165|, v229, v227
.LBB0_160:
	v_cvt_pk_bf16_f32 v166, v162, v163
	v_cvt_pk_bf16_f32 v167, v160, v161
	v_cvt_pk_bf16_f32 v168, v140, v141
	v_cvt_pk_bf16_f32 v169, v164, v165
	v_pk_mul_f32 v[140:141], v[4:5], v[138:139] op_sel_hi:[1,0]
	v_pk_mul_f32 v[160:161], v[2:3], v[138:139] op_sel_hi:[1,0]
	v_pk_mul_f32 v[162:163], v[8:9], v[138:139] op_sel_hi:[1,0]
	s_and_b64 vcc, exec, s[6:7]
	v_pk_mul_f32 v[164:165], v[6:7], v[138:139] op_sel_hi:[1,0]
	global_store_dwordx4 v[158:159], v[166:169], off offset:64
	s_cbranch_vccnz .LBB0_162
; __device__ __forceinline__ f32x2 gelu_pk(f32x2 v) {
;     const f32x2 av = __builtin_elementwise_abs(v), d = av * 0.2316418882f + 1.0f;
;     f32x2 t; t.x = __builtin_amdgcn_rcpf(d.x); t.y = __builtin_amdgcn_rcpf(d.y);
;     f32x2 q = t * 0.5307027145f + (-0.7265760135f); q = q * t + 0.7107068705f; q = q * t + (-0.142248368f); q = q * t + 0.127414796f; q = q * t;
;     const f32x2 s = (v * v) * (-0.72134752044f);
;     f32x2 e; e.x = __builtin_amdgcn_exp2f(s.x); e.y = __builtin_amdgcn_exp2f(s.y);
;     const f32x2 m = v * (q * e), r = v - m;
;     f32x2 o; o.x = v.x < 0.f ? m.x : r.x; o.y = v.y < 0.f ? m.y : r.y; return o;
; }
	v_fma_f32 v220, |v160|, s88, 1.0
	v_fma_f32 v221, |v161|, s88, 1.0
	v_fma_f32 v226, |v140|, s88, 1.0
	v_fma_f32 v227, |v141|, s88, 1.0
	v_pk_mul_f32 v[224:225], v[160:161], v[160:161]
	v_pk_mul_f32 v[230:231], v[140:141], v[140:141]
	v_rcp_f32_e32 v220, v220
	v_rcp_f32_e32 v221, v221
	v_rcp_f32_e32 v226, v226
	v_rcp_f32_e32 v227, v227
	v_pk_mul_f32 v[224:225], v[224:225], s[72:73] op_sel_hi:[1,0]
	v_pk_mul_f32 v[230:231], v[230:231], s[72:73] op_sel_hi:[1,0]
	v_pk_fma_f32 v[222:223], v[220:221], s[90:91], v[232:233] op_sel_hi:[1,0,0]
	v_pk_fma_f32 v[228:229], v[226:227], s[90:91], v[232:233] op_sel_hi:[1,0,0]
	v_exp_f32_e32 v224, v224
	v_exp_f32_e32 v225, v225
	v_exp_f32_e32 v230, v230
	v_exp_f32_e32 v231, v231
	v_pk_fma_f32 v[222:223], v[220:221], v[222:223], s[94:95] op_sel_hi:[1,1,0]
	v_pk_fma_f32 v[228:229], v[226:227], v[228:229], s[94:95] op_sel_hi:[1,1,0]
	v_pk_fma_f32 v[222:223], v[220:221], v[222:223], s[96:97] op_sel_hi:[1,1,0]
	v_pk_fma_f32 v[228:229], v[226:227], v[228:229], s[96:97] op_sel_hi:[1,1,0]
	v_pk_fma_f32 v[222:223], v[220:221], v[222:223], s[98:99] op_sel_hi:[1,1,0]
	v_pk_fma_f32 v[228:229], v[226:227], v[228:229], s[98:99] op_sel_hi:[1,1,0]
	v_pk_mul_f32 v[222:223], v[220:221], v[222:223]
	v_pk_mul_f32 v[228:229], v[226:227], v[228:229]
	v_pk_mul_f32 v[222:223], v[224:225], v[222:223]
	v_pk_mul_f32 v[228:229], v[230:231], v[228:229]
	v_max_f32_e32 v220, 0, v160
	v_max_f32_e32 v221, 0, v161
	v_max_f32_e32 v226, 0, v140
	v_max_f32_e32 v227, 0, v141
	v_fma_f32 v160, -|v160|, v222, v220
	v_fma_f32 v161, -|v161|, v223, v221
	v_fma_f32 v140, -|v140|, v228, v226
	v_fma_f32 v141, -|v141|, v229, v227
	v_fma_f32 v220, |v164|, s88, 1.0
	v_fma_f32 v221, |v165|, s88, 1.0
	v_fma_f32 v226, |v162|, s88, 1.0
	v_fma_f32 v227, |v163|, s88, 1.0
	v_pk_mul_f32 v[224:225], v[164:165], v[164:165]
	v_pk_mul_f32 v[230:231], v[162:163], v[162:163]
	v_rcp_f32_e32 v220, v220
	v_rcp_f32_e32 v221, v221
	v_rcp_f32_e32 v226, v226
	v_rcp_f32_e32 v227, v227
	v_pk_mul_f32 v[224:225], v[224:225], s[72:73] op_sel_hi:[1,0]
	v_pk_mul_f32 v[230:231], v[230:231], s[72:73] op_sel_hi:[1,0]
	v_pk_fma_f32 v[222:223], v[220:221], s[90:91], v[232:233] op_sel_hi:[1,0,0]
	v_pk_fma_f32 v[228:229], v[226:227], s[90:91], v[232:233] op_sel_hi:[1,0,0]
	v_exp_f32_e32 v224, v224
	v_exp_f32_e32 v225, v225
	v_exp_f32_e32 v230, v230
	v_exp_f32_e32 v231, v231
	v_pk_fma_f32 v[222:223], v[220:221], v[222:223], s[94:95] op_sel_hi:[1,1,0]
	v_pk_fma_f32 v[228:229], v[226:227], v[228:229], s[94:95] op_sel_hi:[1,1,0]
	v_pk_fma_f32 v[222:223], v[220:221], v[222:223], s[96:97] op_sel_hi:[1,1,0]
	v_pk_fma_f32 v[228:229], v[226:227], v[228:229], s[96:97] op_sel_hi:[1,1,0]
	v_pk_fma_f32 v[222:223], v[220:221], v[222:223], s[98:99] op_sel_hi:[1,1,0]
	v_pk_fma_f32 v[228:229], v[226:227], v[228:229], s[98:99] op_sel_hi:[1,1,0]
	v_pk_mul_f32 v[222:223], v[220:221], v[222:223]
	v_pk_mul_f32 v[228:229], v[226:227], v[228:229]
	v_pk_mul_f32 v[222:223], v[224:225], v[222:223]
	v_pk_mul_f32 v[228:229], v[230:231], v[228:229]
	v_max_f32_e32 v220, 0, v164
	v_max_f32_e32 v221, 0, v165
	v_max_f32_e32 v226, 0, v162
	v_max_f32_e32 v227, 0, v163
	v_fma_f32 v164, -|v164|, v222, v220
	v_fma_f32 v165, -|v165|, v223, v221
	v_fma_f32 v162, -|v162|, v228, v226
	v_fma_f32 v163, -|v163|, v229, v227
; __device__ __forceinline__ unsigned pk_bf16(float lo, float hi) { f32x2 v = {lo, hi}; bf16x2_t b = __builtin_convertvector(v, bf16x2_t); return __builtin_bit_cast(unsigned, b); }
; __device__ __forceinline__ f32x4 gelu4(f32x4 v) { f32x2 a = gelu_pk((f32x2){v[0], v[1]}), b = gelu_pk((f32x2){v[2], v[3]}); return (f32x4){a.x, a.y, b.x, b.y}; }
; __device__ __forceinline__ f32x2 gelu_pk(f32x2 v) {
;     const f32x2 av = __builtin_elementwise_abs(v), d = av * 0.2316418882f + 1.0f;
;     f32x2 t; t.x = __builtin_amdgcn_rcpf(d.x); t.y = __builtin_amdgcn_rcpf(d.y);
;     f32x2 q = t * 0.5307027145f + (-0.7265760135f); q = q * t + 0.7107068705f; q = q * t + (-0.142248368f); q = q * t + 0.127414796f; q = q * t;
;     const f32x2 s = (v * v) * (-0.72134752044f);
;     f32x2 e; e.x = __builtin_amdgcn_exp2f(s.x); e.y = __builtin_amdgcn_exp2f(s.y);
;     const f32x2 m = v * (q * e), r = v - m;
;     f32x2 o; o.x = v.x < 0.f ? m.x : r.x; o.y = v.y < 0.f ? m.y : r.y; return o;
; }
;     __device__ __forceinline__ void operator()(const f32x4 (&acc)[2][2][4][2], const Unit& u, int wr, int wc, int fr, int fq, float rp0, float rp1, const f32x4& raw0, const f32x4& raw1, float& rn0, float& rn1) const {
;     ...
;                 for (int m = 0; m < 4; ++m) {
;                     const int roff = ai * HALF + m * 16; const float r = rs[m];
; #pragma unroll
;                     for (int bj = 0; bj < 2; ++bj) {
;                         f32x4 v0 = acc[ai][bj][m][0] * r, v1 = acc[ai][bj][m][1] * r;
;                         if (gel) { v0 = gelu4(v0); v1 = gelu4(v1); }
;                         u32x4 w; w.x = pk_bf16(v0[0], v0[1]); w.y = pk_bf16(v0[2], v0[3]); w.z = pk_bf16(v1[0], v1[1]); w.w = pk_bf16(v1[2], v1[3]);
;                         *(u32x4*)(base + (size_t)roff * ld + bj * 32) = w;
;                     }
.LBB0_162:
	s_nop 0
	v_lshl_add_u64 v[166:167], v[158:159], 0, s[76:77]
	v_cvt_pk_bf16_f32 v158, v160, v161
	v_cvt_pk_bf16_f32 v159, v140, v141
	v_cvt_pk_bf16_f32 v160, v164, v165
	v_cvt_pk_bf16_f32 v161, v162, v163
	v_mov_b32_e32 v139, v138
	global_store_dwordx4 v[166:167], v[158:161], off
	s_and_b64 vcc, exec, s[6:7]
	v_pk_mul_f32 v[162:163], v[22:23], v[138:139]
	v_mov_b32_e32 v160, v138
	v_mov_b32_e32 v161, v138
	v_pk_mul_f32 v[140:141], v[20:21], v[160:161]
	v_pk_mul_f32 v[158:159], v[18:19], v[138:139]
	v_pk_mul_f32 v[160:161], v[24:25], v[160:161]
	s_cbranch_vccnz .LBB0_164
	v_fma_f32 v220, |v158|, s88, 1.0
	v_fma_f32 v221, |v159|, s88, 1.0
	v_fma_f32 v226, |v140|, s88, 1.0
	v_fma_f32 v227, |v141|, s88, 1.0
	v_pk_mul_f32 v[224:225], v[158:159], v[158:159]
	v_pk_mul_f32 v[230:231], v[140:141], v[140:141]
	v_rcp_f32_e32 v220, v220
	v_rcp_f32_e32 v221, v221
	v_rcp_f32_e32 v226, v226
	v_rcp_f32_e32 v227, v227
	v_pk_mul_f32 v[224:225], v[224:225], s[72:73] op_sel_hi:[1,0]
	v_pk_mul_f32 v[230:231], v[230:231], s[72:73] op_sel_hi:[1,0]
	v_pk_fma_f32 v[222:223], v[220:221], s[90:91], v[232:233] op_sel_hi:[1,0,0]
	v_pk_fma_f32 v[228:229], v[226:227], s[90:91], v[232:233] op_sel_hi:[1,0,0]
	v_exp_f32_e32 v224, v224
	v_exp_f32_e32 v225, v225
	v_exp_f32_e32 v230, v230
	v_exp_f32_e32 v231, v231
	v_pk_fma_f32 v[222:223], v[220:221], v[222:223], s[94:95] op_sel_hi:[1,1,0]
	v_pk_fma_f32 v[228:229], v[226:227], v[228:229], s[94:95] op_sel_hi:[1,1,0]
	v_pk_fma_f32 v[222:223], v[220:221], v[222:223], s[96:97] op_sel_hi:[1,1,0]
	v_pk_fma_f32 v[228:229], v[226:227], v[228:229], s[96:97] op_sel_hi:[1,1,0]
	v_pk_fma_f32 v[222:223], v[220:221], v[222:223], s[98:99] op_sel_hi:[1,1,0]
	v_pk_fma_f32 v[228:229], v[226:227], v[228:229], s[98:99] op_sel_hi:[1,1,0]
	v_pk_mul_f32 v[222:223], v[220:221], v[222:223]
	v_pk_mul_f32 v[228:229], v[226:227], v[228:229]
	v_pk_mul_f32 v[222:223], v[224:225], v[222:223]
	v_pk_mul_f32 v[228:229], v[230:231], v[228:229]
	v_max_f32_e32 v220, 0, v158
	v_max_f32_e32 v221, 0, v159
	v_max_f32_e32 v226, 0, v140
	v_max_f32_e32 v227, 0, v141
	v_fma_f32 v158, -|v158|, v222, v220
	v_fma_f32 v159, -|v159|, v223, v221
	v_fma_f32 v140, -|v140|, v228, v226
	v_fma_f32 v141, -|v141|, v229, v227
	v_fma_f32 v220, |v162|, s88, 1.0
	v_fma_f32 v221, |v163|, s88, 1.0
	v_fma_f32 v226, |v160|, s88, 1.0
	v_fma_f32 v227, |v161|, s88, 1.0
	v_pk_mul_f32 v[224:225], v[162:163], v[162:163]
	v_pk_mul_f32 v[230:231], v[160:161], v[160:161]
	v_rcp_f32_e32 v220, v220
	v_rcp_f32_e32 v221, v221
	v_rcp_f32_e32 v226, v226
	v_rcp_f32_e32 v227, v227
	v_pk_mul_f32 v[224:225], v[224:225], s[72:73] op_sel_hi:[1,0]
	v_pk_mul_f32 v[230:231], v[230:231], s[72:73] op_sel_hi:[1,0]
	v_pk_fma_f32 v[222:223], v[220:221], s[90:91], v[232:233] op_sel_hi:[1,0,0]
	v_pk_fma_f32 v[228:229], v[226:227], s[90:91], v[232:233] op_sel_hi:[1,0,0]
	v_exp_f32_e32 v224, v224
	v_exp_f32_e32 v225, v225
	v_exp_f32_e32 v230, v230
	v_exp_f32_e32 v231, v231
	v_pk_fma_f32 v[222:223], v[220:221], v[222:223], s[94:95] op_sel_hi:[1,1,0]
	v_pk_fma_f32 v[228:229], v[226:227], v[228:229], s[94:95] op_sel_hi:[1,1,0]
	v_pk_fma_f32 v[222:223], v[220:221], v[222:223], s[96:97] op_sel_hi:[1,1,0]
	v_pk_fma_f32 v[228:229], v[226:227], v[228:229], s[96:97] op_sel_hi:[1,1,0]
	v_pk_fma_f32 v[222:223], v[220:221], v[222:223], s[98:99] op_sel_hi:[1,1,0]
	v_pk_fma_f32 v[228:229], v[226:227], v[228:229], s[98:99] op_sel_hi:[1,1,0]
	v_pk_mul_f32 v[222:223], v[220:221], v[222:223]
	v_pk_mul_f32 v[228:229], v[226:227], v[228:229]
	v_pk_mul_f32 v[222:223], v[224:225], v[222:223]
	v_pk_mul_f32 v[228:229], v[230:231], v[228:229]
	v_max_f32_e32 v220, 0, v162
	v_max_f32_e32 v221, 0, v163
	v_max_f32_e32 v226, 0, v160
	v_max_f32_e32 v227, 0, v161
	v_fma_f32 v162, -|v162|, v222, v220
	v_fma_f32 v163, -|v163|, v223, v221
	v_fma_f32 v160, -|v160|, v228, v226
	v_fma_f32 v161, -|v161|, v229, v227
